# in-proj epilogue row-stat exchanges via permlane swaps; attention packed f32 ops split into scalar pairs
# speedup vs baseline: 1.0201x; 1.0056x over previous
; #define LAS __attribute__((address_space(3)))
; #define MFMA32(a, b, c) __builtin_amdgcn_mfma_f32_32x32x16_bf16((a), (b), (c), 0, 0, 0)
; template <int MODE>
; __device__ __forceinline__ void attn_item(LAS unsigned char* lds, const AttnArgs& a, const int tid) {
;     ...
;             constexpr int KD = AT_KD, VD = AT_VD;
;             bf16x8 kf[KD];
;     ...
; #pragma unroll
;             for (int i = 0; i < KD; ++i) kf[i] = AT_KLD(i);
; #pragma unroll
;             for (int i = 0; i < 2 * NKS; ++i) { s[i & 1] = MFMA32(kf[i % KD], qf[i >> 1], s[i & 1]); if (i + KD < 2 * NKS) kf[i % KD] = AT_KLD(i + KD); }
;     ...
;             bf16x8 vf[VD];
;     ...
; #pragma unroll
;             for (int j = 0; j < VD; ++j) AT_VLD(j);
;             const float sc = a.sc;
;             const bool diag = (MODE == 1) && (t * 64 + 63 > qw0);
;             const bool near = (MODE == 2) && (t >= tw - 2);
;             bf16x8 pf[2];
; #pragma unroll
;             for (int kt = 0; kt < 2; ++kt) {
;                 if (MODE == 1) {
;                     const LAS float* csb = (const LAS float*)(lds + A_CS) + t * 64 + 32 * kt + 4 * h;
;                     const int mb = t * 64 + 32 * kt + 4 * h - (qw0 + r);
; #pragma unroll
;                     for (int g = 0; g < 4; ++g) { const f32x4 cv = *(const LAS f32x4*)(csb + 8 * g);
; #pragma unroll
;                         for (int e = 0; e < 4; ++e) { float x = fmaf(s[kt][4 * g + e], sc, addc) + cv[e]; if (diag && (mb + 8 * g + e > 0)) x = -1e30f; s[kt][4 * g + e] = x; } }
;                 } else if (MODE == 2) {
;                     if (near) {
;                         const LAS float* lut = (const LAS float*)(lds + A_LUT) + (t * 64 + 32 * kt + 4 * h - (qw0 + r) + 191);
; #pragma unroll
;                         for (int i = 0; i < 16; ++i) s[kt][i] = fmaf(s[kt][i], sc, lut[8 * (i >> 2) + (i & 3)]);
;                     } else {
; #pragma unroll
;                         for (int i = 0; i < 16; ++i) s[kt][i] = fmaf(s[kt][i], sc, addc);
;                     }
;                 } else {
; #pragma unroll
;                     for (int i = 0; i < 16; ++i) s[kt][i] = fmaf(s[kt][i], sc, addc);
;                 }
.LBB0_21:
	s_cmp_gt_u32 s35, s43
	s_cbranch_scc1 .LBB0_31
	ds_read_b128 v[2:5], v184
	ds_read_b128 v[6:9], v184 offset:8192
	ds_read_b128 v[10:13], v185
	ds_read_b128 v[140:143], v185 offset:8192
	s_cmp_ge_i32 s35, s48
	s_waitcnt lgkmcnt(3)
	v_mfma_f32_32x32x16_bf16 v[96:111], v[2:5], v[116:119], 0
	ds_read_b128 v[2:5], v186
	s_cselect_b64 s[10:11], -1, 0
	s_mov_b64 s[12:13], -1
	s_and_b64 vcc, exec, s[10:11]
	s_waitcnt lgkmcnt(3)
	v_mfma_f32_32x32x16_bf16 v[80:95], v[6:9], v[116:119], 0
	ds_read_b128 v[6:9], v186 offset:8192
	s_waitcnt lgkmcnt(3)
	v_mfma_f32_32x32x16_bf16 v[96:111], v[10:13], v[120:123], v[96:111]
	ds_read_b128 v[10:13], v187
	s_waitcnt lgkmcnt(3)
	v_mfma_f32_32x32x16_bf16 v[80:95], v[140:143], v[120:123], v[80:95]
	ds_read_b128 v[140:143], v187 offset:8192
	s_waitcnt lgkmcnt(3)
	v_mfma_f32_32x32x16_bf16 v[96:111], v[2:5], v[124:127], v[96:111]
	s_waitcnt lgkmcnt(2)
	v_mfma_f32_32x32x16_bf16 v[80:95], v[6:9], v[124:127], v[80:95]
	s_waitcnt lgkmcnt(1)
	v_mfma_f32_32x32x16_bf16 v[96:111], v[10:13], v[128:131], v[96:111]
	ds_read_b64_tr_b16 v[10:11], v169 offset:16384
	ds_read_b64_tr_b16 v[12:13], v170 offset:16384
	ds_read_b64_tr_b16 v[6:7], v171 offset:16384
	ds_read_b64_tr_b16 v[8:9], v172 offset:16384
	ds_read_b64_tr_b16 v[2:3], v173 offset:16384
	ds_read_b64_tr_b16 v[4:5], v179 offset:16384
	s_waitcnt lgkmcnt(6)
	v_mfma_f32_32x32x16_bf16 v[80:95], v[140:143], v[128:131], v[80:95]
	s_cbranch_vccz .LBB0_24
	ds_read2_b32 v[14:15], v135 offset1:1
	ds_read2_b32 v[140:141], v135 offset0:2 offset1:3
	ds_read2_b32 v[142:143], v135 offset0:8 offset1:9
	ds_read2_b32 v[144:145], v135 offset0:10 offset1:11
	ds_read2_b32 v[146:147], v135 offset0:16 offset1:17
	ds_read2_b32 v[148:149], v135 offset0:18 offset1:19
	ds_read2_b32 v[150:151], v135 offset0:24 offset1:25
	ds_read2_b32 v[152:153], v135 offset0:26 offset1:27
	s_waitcnt lgkmcnt(7)
	v_fma_f32 v14, v96, s40, v14
	v_fma_f32 v15, v97, s40, v15
	s_waitcnt lgkmcnt(6)
	v_fma_f32 v140, v98, s40, v140
	v_fma_f32 v141, v99, s40, v141
	s_waitcnt lgkmcnt(5)
	v_fma_f32 v142, v100, s40, v142
	v_fma_f32 v143, v101, s40, v143
	s_waitcnt lgkmcnt(4)
	v_fma_f32 v144, v102, s40, v144
	v_fma_f32 v145, v103, s40, v145
	s_waitcnt lgkmcnt(3)
	v_fma_f32 v146, v104, s40, v146
	v_fma_f32 v147, v105, s40, v147
	s_waitcnt lgkmcnt(2)
	v_fma_f32 v148, v106, s40, v148
	v_fma_f32 v149, v107, s40, v149
	s_waitcnt lgkmcnt(1)
	v_fma_f32 v150, v108, s40, v150
	v_fma_f32 v151, v109, s40, v151
	s_waitcnt lgkmcnt(0)
	v_fmac_f32_e32 v152, 0x3e38aa3b, v110
	s_mov_b64 s[12:13], 0
.LBB0_24:
	s_andn2_b64 vcc, exec, s[12:13]
	s_cbranch_vccnz .LBB0_26
	s_nop 0
	v_fma_f32 v14, v96, s40, v136
	v_fma_f32 v15, v97, s40, v137
	v_fma_f32 v140, v98, s40, v136
	v_fma_f32 v141, v99, s40, v137
	v_fma_f32 v142, v100, s40, v136
	v_fma_f32 v143, v101, s40, v137
	v_fma_f32 v144, v102, s40, v136
	v_fma_f32 v145, v103, s40, v137
	v_fma_f32 v146, v104, s40, v136
	v_fma_f32 v147, v105, s40, v137
	v_fma_f32 v148, v106, s40, v136
	v_fma_f32 v149, v107, s40, v137
	v_fma_f32 v150, v108, s40, v136
	v_fma_f32 v151, v109, s40, v137
	v_fmamk_f32 v152, v110, 0x3e38aa3b, v136
	v_mov_b32_e32 v153, v136
; #define LAS __attribute__((address_space(3)))
; #define MFMA32(a, b, c) __builtin_amdgcn_mfma_f32_32x32x16_bf16((a), (b), (c), 0, 0, 0)
; __device__ __forceinline__ unsigned pk2(float lo, float hi) { const f32x2v v = {lo, hi}; return __builtin_bit_cast(unsigned, __builtin_convertvector(v, bf16x2v)); }
; __device__ __forceinline__ float fast_exp2(float x) { return __builtin_amdgcn_exp2f(x); }
; template <int MODE>
; __device__ __forceinline__ void attn_item(LAS unsigned char* lds, const AttnArgs& a, const int tid) {
;     ...
;                 } else if (MODE == 2) {
;                     if (near) {
;                         const LAS float* lut = (const LAS float*)(lds + A_LUT) + (t * 64 + 32 * kt + 4 * h - (qw0 + r) + 191);
; #pragma unroll
;                         for (int i = 0; i < 16; ++i) s[kt][i] = fmaf(s[kt][i], sc, lut[8 * (i >> 2) + (i & 3)]);
;                     } else {
; #pragma unroll
;                         for (int i = 0; i < 16; ++i) s[kt][i] = fmaf(s[kt][i], sc, addc);
;                     }
;                 } else {
; #pragma unroll
;                     for (int i = 0; i < 16; ++i) s[kt][i] = fmaf(s[kt][i], sc, addc);
;                 }
;                 float ls = 0.f;
; #pragma unroll
;                 for (int i = 0; i < 16; ++i) { const float pv = fast_exp2(s[kt][i]); s[kt][i] = pv; ls += pv; }
;                 l += ls;
; #pragma unroll
;                 for (int ss = 0; ss < 2; ++ss) { u32x4 w;
;                     w.x = pk2(s[kt][8 * ss + 0], s[kt][8 * ss + 1]); w.y = pk2(s[kt][8 * ss + 2], s[kt][8 * ss + 3]);
;                     w.z = pk2(s[kt][8 * ss + 4], s[kt][8 * ss + 5]); w.w = pk2(s[kt][8 * ss + 6], s[kt][8 * ss + 7]);
;                     pf[ss] = __builtin_bit_cast(bf16x8, w); }
; #pragma unroll
;                 for (int jj = 0; jj < 8; ++jj) { const int j = 8 * kt + jj;
;                     o[jj & 3] = MFMA32(vf[j % VD], pf[jj >> 2], o[jj & 3]);
;                     if (j + VD < 16) AT_VLD(j + VD); }
.LBB0_26:
	v_exp_f32_e32 v188, v14
	v_exp_f32_e32 v189, v15
	v_exp_f32_e32 v190, v140
	v_exp_f32_e32 v191, v141
	v_exp_f32_e32 v192, v142
	v_exp_f32_e32 v193, v143
	v_exp_f32_e32 v140, v144
	v_exp_f32_e32 v141, v145
	v_exp_f32_e32 v143, v147
	v_exp_f32_e32 v144, v148
	v_cvt_pk_bf16_f32 v96, v188, v189
	v_cvt_pk_bf16_f32 v97, v190, v191
	v_cvt_pk_bf16_f32 v98, v192, v193
	v_cvt_pk_bf16_f32 v99, v140, v141
	v_add_u32_e32 v147, 0, v165
	v_add_u32_e32 v148, 0, v166
	s_waitcnt lgkmcnt(4)
	v_mfma_f32_32x32x16_bf16 v[64:79], v[10:13], v[96:99], v[64:79]
	ds_read_b64_tr_b16 v[10:11], v147 offset:16384
	ds_read_b64_tr_b16 v[12:13], v148 offset:16384
	v_fmac_f32_e32 v153, 0x3e38aa3b, v111
	v_exp_f32_e32 v142, v146
	v_exp_f32_e32 v145, v149
	v_exp_f32_e32 v146, v150
	v_exp_f32_e32 v111, v151
	s_waitcnt lgkmcnt(4)
	v_mfma_f32_32x32x16_bf16 v[48:63], v[6:9], v[96:99], v[48:63]
	v_exp_f32_e32 v0, v152
	v_exp_f32_e32 v110, v153
	ds_read_b64_tr_b16 v[6:7], v169 offset:20480
	ds_read_b64_tr_b16 v[8:9], v170 offset:20480
	v_cvt_pk_bf16_f32 v100, v142, v143
	v_cvt_pk_bf16_f32 v101, v144, v145
	v_cvt_pk_bf16_f32 v102, v146, v111
	v_cvt_pk_bf16_f32 v103, v0, v110
	s_waitcnt lgkmcnt(4)
	v_mfma_f32_32x32x16_bf16 v[32:47], v[2:5], v[96:99], v[32:47]
	ds_read_b64_tr_b16 v[2:3], v171 offset:20480
	ds_read_b64_tr_b16 v[4:5], v172 offset:20480
	s_mov_b64 s[12:13], -1
	s_andn2_b64 vcc, exec, s[10:11]
	s_waitcnt lgkmcnt(4)
	v_mfma_f32_32x32x16_bf16 v[16:31], v[10:13], v[96:99], v[16:31]
	ds_read_b64_tr_b16 v[10:11], v173 offset:20480
	ds_read_b64_tr_b16 v[12:13], v179 offset:20480
	ds_read_b64_tr_b16 v[96:97], v147 offset:20480
	ds_read_b64_tr_b16 v[98:99], v148 offset:20480
	s_waitcnt lgkmcnt(6)
	v_mfma_f32_32x32x16_bf16 v[64:79], v[6:9], v[100:103], v[64:79]
	s_waitcnt lgkmcnt(4)
	v_mfma_f32_32x32x16_bf16 v[48:63], v[2:5], v[100:103], v[48:63]
	ds_read_b64_tr_b16 v[2:3], v169 offset:24576
	ds_read_b64_tr_b16 v[4:5], v170 offset:24576
	ds_read_b64_tr_b16 v[6:7], v171 offset:24576
	ds_read_b64_tr_b16 v[8:9], v172 offset:24576
	s_waitcnt lgkmcnt(6)
	v_mfma_f32_32x32x16_bf16 v[32:47], v[10:13], v[100:103], v[32:47]
	ds_read_b64_tr_b16 v[10:11], v173 offset:24576
	ds_read_b64_tr_b16 v[12:13], v179 offset:24576
	s_waitcnt lgkmcnt(6)
	v_mfma_f32_32x32x16_bf16 v[16:31], v[96:99], v[100:103], v[16:31]
	s_cbranch_vccnz .LBB0_28
	ds_read2_b32 v[14:15], v135 offset0:32 offset1:33
	ds_read2_b32 v[96:97], v135 offset0:34 offset1:35
	ds_read2_b32 v[98:99], v135 offset0:40 offset1:41
	ds_read2_b32 v[100:101], v135 offset0:42 offset1:43
	s_mov_b64 s[12:13], 0
	s_waitcnt lgkmcnt(3)
	v_fma_f32 v106, v80, s40, v14
	v_fma_f32 v107, v81, s40, v15
	s_waitcnt lgkmcnt(2)
	v_fma_f32 v104, v82, s40, v96
	v_fma_f32 v105, v83, s40, v97
	ds_read2_b32 v[14:15], v135 offset0:48 offset1:49
	ds_read2_b32 v[96:97], v135 offset0:50 offset1:51
	ds_read2_b32 v[150:151], v135 offset0:56 offset1:57
	ds_read2_b32 v[152:153], v135 offset0:58 offset1:59
	s_waitcnt lgkmcnt(5)
	v_fma_f32 v102, v84, s40, v98
	v_fma_f32 v103, v85, s40, v99
	s_waitcnt lgkmcnt(4)
	v_fma_f32 v108, v86, s40, v100
	v_fma_f32 v109, v87, s40, v101
	s_waitcnt lgkmcnt(3)
	v_fma_f32 v98, v88, s40, v14
	v_fma_f32 v99, v89, s40, v15
	s_waitcnt lgkmcnt(2)
	v_fma_f32 v100, v90, s40, v96
	v_fma_f32 v101, v91, s40, v97
	s_waitcnt lgkmcnt(1)
	v_fma_f32 v96, v92, s40, v150
	v_fma_f32 v97, v93, s40, v151
	s_waitcnt lgkmcnt(0)
	v_fma_f32 v14, v94, s40, v152
	v_fma_f32 v15, v95, s40, v153
.LBB0_28:
	s_andn2_b64 vcc, exec, s[12:13]
	s_cbranch_vccnz .LBB0_30
	v_fma_f32 v106, v80, s40, v136
	v_fma_f32 v107, v81, s40, v137
	v_fma_f32 v104, v82, s40, v136
	v_fma_f32 v105, v83, s40, v137
	v_fma_f32 v102, v84, s40, v136
	v_fma_f32 v103, v85, s40, v137
	v_fma_f32 v108, v86, s40, v136
	v_fma_f32 v109, v87, s40, v137
	v_fma_f32 v98, v88, s40, v136
	v_fma_f32 v99, v89, s40, v137
	v_fma_f32 v100, v90, s40, v136
	v_fma_f32 v101, v91, s40, v137
	v_fma_f32 v96, v92, s40, v136
	v_fma_f32 v97, v93, s40, v137
	v_fma_f32 v14, v94, s40, v136
	v_fma_f32 v15, v95, s40, v137

; #define LAS __attribute__((address_space(3)))
; #define MFMA32(a, b, c) __builtin_amdgcn_mfma_f32_32x32x16_bf16((a), (b), (c), 0, 0, 0)
; template <int MODE>
; __device__ __forceinline__ void attn_item(LAS unsigned char* lds, const AttnArgs& a, const int tid) {
;     ...
;             constexpr int KD = AT_KD, VD = AT_VD;
;             bf16x8 kf[KD];
;     ...
; #pragma unroll
;             for (int i = 0; i < KD; ++i) kf[i] = AT_KLD(i);
; #pragma unroll
;             for (int i = 0; i < 2 * NKS; ++i) { s[i & 1] = MFMA32(kf[i % KD], qf[i >> 1], s[i & 1]); if (i + KD < 2 * NKS) kf[i % KD] = AT_KLD(i + KD); }
;     ...
;             bf16x8 vf[VD];
;     ...
; #pragma unroll
;             for (int j = 0; j < VD; ++j) AT_VLD(j);
;             const float sc = a.sc;
;             const bool diag = (MODE == 1) && (t * 64 + 63 > qw0);
;             const bool near = (MODE == 2) && (t >= tw - 2);
;             bf16x8 pf[2];
; #pragma unroll
;             for (int kt = 0; kt < 2; ++kt) {
;                 if (MODE == 1) {
;                     const LAS float* csb = (const LAS float*)(lds + A_CS) + t * 64 + 32 * kt + 4 * h;
;                     const int mb = t * 64 + 32 * kt + 4 * h - (qw0 + r);
; #pragma unroll
;                     for (int g = 0; g < 4; ++g) { const f32x4 cv = *(const LAS f32x4*)(csb + 8 * g);
; #pragma unroll
;                         for (int e = 0; e < 4; ++e) { float x = fmaf(s[kt][4 * g + e], sc, addc) + cv[e]; if (diag && (mb + 8 * g + e > 0)) x = -1e30f; s[kt][4 * g + e] = x; } }
;                 } else if (MODE == 2) {
;                     if (near) {
;                         const LAS float* lut = (const LAS float*)(lds + A_LUT) + (t * 64 + 32 * kt + 4 * h - (qw0 + r) + 191);
; #pragma unroll
;                         for (int i = 0; i < 16; ++i) s[kt][i] = fmaf(s[kt][i], sc, lut[8 * (i >> 2) + (i & 3)]);
;                     } else {
; #pragma unroll
;                         for (int i = 0; i < 16; ++i) s[kt][i] = fmaf(s[kt][i], sc, addc);
;                     }
;                 } else {
; #pragma unroll
;                     for (int i = 0; i < 16; ++i) s[kt][i] = fmaf(s[kt][i], sc, addc);
;                 }
.LBB0_33:
	s_cmp_ge_u32 s35, s43
	s_cbranch_scc1 .LBB0_18
	ds_read_b128 v[2:5], v184 offset:32768
	ds_read_b128 v[6:9], v184 offset:40960
	ds_read_b128 v[10:13], v185 offset:32768
	ds_read_b128 v[140:143], v185 offset:40960
	s_cmp_ge_i32 s55, s48
	s_waitcnt lgkmcnt(3)
	v_mfma_f32_32x32x16_bf16 v[96:111], v[2:5], v[116:119], 0
	ds_read_b128 v[2:5], v186 offset:32768
	s_mov_b64 s[14:15], -1
	s_cselect_b64 s[12:13], -1, 0
	s_cmp_lt_i32 s55, s48
	s_waitcnt lgkmcnt(3)
	v_mfma_f32_32x32x16_bf16 v[80:95], v[6:9], v[116:119], 0
	ds_read_b128 v[6:9], v186 offset:40960
	s_waitcnt lgkmcnt(3)
	v_mfma_f32_32x32x16_bf16 v[96:111], v[10:13], v[120:123], v[96:111]
	ds_read_b128 v[10:13], v187 offset:32768
	s_waitcnt lgkmcnt(3)
	v_mfma_f32_32x32x16_bf16 v[80:95], v[140:143], v[120:123], v[80:95]
	ds_read_b128 v[140:143], v187 offset:40960
	s_waitcnt lgkmcnt(3)
	v_mfma_f32_32x32x16_bf16 v[96:111], v[2:5], v[124:127], v[96:111]
	s_waitcnt lgkmcnt(2)
	v_mfma_f32_32x32x16_bf16 v[80:95], v[6:9], v[124:127], v[80:95]
	s_waitcnt lgkmcnt(1)
	v_mfma_f32_32x32x16_bf16 v[96:111], v[10:13], v[128:131], v[96:111]
	ds_read_b64_tr_b16 v[10:11], v169 offset:49152
	ds_read_b64_tr_b16 v[12:13], v170 offset:49152
	ds_read_b64_tr_b16 v[6:7], v171 offset:49152
	ds_read_b64_tr_b16 v[8:9], v172 offset:49152
	ds_read_b64_tr_b16 v[2:3], v173 offset:49152
	ds_read_b64_tr_b16 v[4:5], v179 offset:49152
	s_waitcnt lgkmcnt(6)
	v_mfma_f32_32x32x16_bf16 v[80:95], v[140:143], v[128:131], v[80:95]
	s_cbranch_scc1 .LBB0_36
	ds_read2_b32 v[14:15], v135 offset0:64 offset1:65
	ds_read2_b32 v[140:141], v135 offset0:66 offset1:67
	ds_read2_b32 v[142:143], v135 offset0:72 offset1:73
	ds_read2_b32 v[144:145], v135 offset0:74 offset1:75
	ds_read2_b32 v[146:147], v135 offset0:80 offset1:81
	ds_read2_b32 v[148:149], v135 offset0:82 offset1:83
	ds_read2_b32 v[150:151], v135 offset0:88 offset1:89
	ds_read2_b32 v[152:153], v135 offset0:90 offset1:91
	s_waitcnt lgkmcnt(7)
	v_fma_f32 v14, v96, s40, v14
	v_fma_f32 v15, v97, s40, v15
	s_waitcnt lgkmcnt(6)
	v_fma_f32 v140, v98, s40, v140
	v_fma_f32 v141, v99, s40, v141
	s_waitcnt lgkmcnt(5)
	v_fma_f32 v142, v100, s40, v142
	v_fma_f32 v143, v101, s40, v143
	s_waitcnt lgkmcnt(4)
	v_fma_f32 v144, v102, s40, v144
	v_fma_f32 v145, v103, s40, v145
	s_waitcnt lgkmcnt(3)
	v_fma_f32 v146, v104, s40, v146
	v_fma_f32 v147, v105, s40, v147
	s_waitcnt lgkmcnt(2)
	v_fma_f32 v148, v106, s40, v148
	v_fma_f32 v149, v107, s40, v149
	s_waitcnt lgkmcnt(1)
	v_fma_f32 v150, v108, s40, v150
	v_fma_f32 v151, v109, s40, v151
	s_waitcnt lgkmcnt(0)
	v_fmac_f32_e32 v152, 0x3e38aa3b, v110
	s_mov_b64 s[14:15], 0
.LBB0_36:
	s_andn2_b64 vcc, exec, s[14:15]
	s_cbranch_vccnz .LBB0_38
	s_nop 0
	v_fma_f32 v14, v96, s40, v136
	v_fma_f32 v15, v97, s40, v137
	v_fma_f32 v140, v98, s40, v136
	v_fma_f32 v141, v99, s40, v137
	v_fma_f32 v142, v100, s40, v136
	v_fma_f32 v143, v101, s40, v137
	v_fma_f32 v144, v102, s40, v136
	v_fma_f32 v145, v103, s40, v137
	v_fma_f32 v146, v104, s40, v136
	v_fma_f32 v147, v105, s40, v137
	v_fma_f32 v148, v106, s40, v136
	v_fma_f32 v149, v107, s40, v137
	v_fma_f32 v150, v108, s40, v136
	v_fma_f32 v151, v109, s40, v137
	v_fmamk_f32 v152, v110, 0x3e38aa3b, v136
	v_mov_b32_e32 v153, v136
; #define LAS __attribute__((address_space(3)))
; #define MFMA32(a, b, c) __builtin_amdgcn_mfma_f32_32x32x16_bf16((a), (b), (c), 0, 0, 0)
; __device__ __forceinline__ unsigned pk2(float lo, float hi) { const f32x2v v = {lo, hi}; return __builtin_bit_cast(unsigned, __builtin_convertvector(v, bf16x2v)); }
; __device__ __forceinline__ float fast_exp2(float x) { return __builtin_amdgcn_exp2f(x); }
; template <int MODE>
; __device__ __forceinline__ void attn_item(LAS unsigned char* lds, const AttnArgs& a, const int tid) {
;     ...
;                 } else if (MODE == 2) {
;                     if (near) {
;                         const LAS float* lut = (const LAS float*)(lds + A_LUT) + (t * 64 + 32 * kt + 4 * h - (qw0 + r) + 191);
; #pragma unroll
;                         for (int i = 0; i < 16; ++i) s[kt][i] = fmaf(s[kt][i], sc, lut[8 * (i >> 2) + (i & 3)]);
;                     } else {
; #pragma unroll
;                         for (int i = 0; i < 16; ++i) s[kt][i] = fmaf(s[kt][i], sc, addc);
;                     }
;                 } else {
; #pragma unroll
;                     for (int i = 0; i < 16; ++i) s[kt][i] = fmaf(s[kt][i], sc, addc);
;                 }
;                 float ls = 0.f;
; #pragma unroll
;                 for (int i = 0; i < 16; ++i) { const float pv = fast_exp2(s[kt][i]); s[kt][i] = pv; ls += pv; }
;                 l += ls;
; #pragma unroll
;                 for (int ss = 0; ss < 2; ++ss) { u32x4 w;
;                     w.x = pk2(s[kt][8 * ss + 0], s[kt][8 * ss + 1]); w.y = pk2(s[kt][8 * ss + 2], s[kt][8 * ss + 3]);
;                     w.z = pk2(s[kt][8 * ss + 4], s[kt][8 * ss + 5]); w.w = pk2(s[kt][8 * ss + 6], s[kt][8 * ss + 7]);
;                     pf[ss] = __builtin_bit_cast(bf16x8, w); }
; #pragma unroll
;                 for (int jj = 0; jj < 8; ++jj) { const int j = 8 * kt + jj;
;                     o[jj & 3] = MFMA32(vf[j % VD], pf[jj >> 2], o[jj & 3]);
;                     if (j + VD < 16) AT_VLD(j + VD); }
.LBB0_38:
	v_exp_f32_e32 v188, v14
	v_exp_f32_e32 v189, v15
	v_exp_f32_e32 v190, v140
	v_exp_f32_e32 v191, v141
	v_exp_f32_e32 v192, v142
	v_exp_f32_e32 v193, v143
	v_exp_f32_e32 v140, v144
	v_exp_f32_e32 v141, v145
	v_exp_f32_e32 v143, v147
	v_exp_f32_e32 v144, v148
	v_cvt_pk_bf16_f32 v96, v188, v189
	v_cvt_pk_bf16_f32 v97, v190, v191
	v_cvt_pk_bf16_f32 v98, v192, v193
	v_cvt_pk_bf16_f32 v99, v140, v141
	v_add_u32_e32 v147, 0, v165
	v_add_u32_e32 v148, 0, v166
	s_waitcnt lgkmcnt(4)
	v_mfma_f32_32x32x16_bf16 v[64:79], v[10:13], v[96:99], v[64:79]
	ds_read_b64_tr_b16 v[10:11], v147 offset:49152
	ds_read_b64_tr_b16 v[12:13], v148 offset:49152
	v_fmac_f32_e32 v153, 0x3e38aa3b, v111
	v_exp_f32_e32 v142, v146
	v_exp_f32_e32 v145, v149
	v_exp_f32_e32 v146, v150
	v_exp_f32_e32 v111, v151
	s_waitcnt lgkmcnt(4)
	v_mfma_f32_32x32x16_bf16 v[48:63], v[6:9], v[96:99], v[48:63]
	v_exp_f32_e32 v0, v152
	v_exp_f32_e32 v110, v153
	ds_read_b64_tr_b16 v[6:7], v169 offset:53248
	ds_read_b64_tr_b16 v[8:9], v170 offset:53248
	v_cvt_pk_bf16_f32 v100, v142, v143
	v_cvt_pk_bf16_f32 v101, v144, v145
	v_cvt_pk_bf16_f32 v102, v146, v111
	v_cvt_pk_bf16_f32 v103, v0, v110
	s_waitcnt lgkmcnt(4)
	v_mfma_f32_32x32x16_bf16 v[32:47], v[2:5], v[96:99], v[32:47]
	ds_read_b64_tr_b16 v[2:3], v171 offset:53248
	ds_read_b64_tr_b16 v[4:5], v172 offset:53248
	s_mov_b64 s[14:15], -1
	s_andn2_b64 vcc, exec, s[12:13]
	s_waitcnt lgkmcnt(4)
	v_mfma_f32_32x32x16_bf16 v[16:31], v[10:13], v[96:99], v[16:31]
	ds_read_b64_tr_b16 v[10:11], v173 offset:53248
	ds_read_b64_tr_b16 v[12:13], v179 offset:53248
	ds_read_b64_tr_b16 v[96:97], v147 offset:53248
	ds_read_b64_tr_b16 v[98:99], v148 offset:53248
	s_waitcnt lgkmcnt(6)
	v_mfma_f32_32x32x16_bf16 v[64:79], v[6:9], v[100:103], v[64:79]
	s_waitcnt lgkmcnt(4)
	v_mfma_f32_32x32x16_bf16 v[48:63], v[2:5], v[100:103], v[48:63]
	ds_read_b64_tr_b16 v[2:3], v169 offset:57344
	ds_read_b64_tr_b16 v[4:5], v170 offset:57344
	ds_read_b64_tr_b16 v[6:7], v171 offset:57344
	ds_read_b64_tr_b16 v[8:9], v172 offset:57344
	s_waitcnt lgkmcnt(6)
	v_mfma_f32_32x32x16_bf16 v[32:47], v[10:13], v[100:103], v[32:47]
	ds_read_b64_tr_b16 v[10:11], v173 offset:57344
	ds_read_b64_tr_b16 v[12:13], v179 offset:57344
	s_waitcnt lgkmcnt(6)
	v_mfma_f32_32x32x16_bf16 v[16:31], v[96:99], v[100:103], v[16:31]
	s_cbranch_vccnz .LBB0_40
	ds_read2_b32 v[14:15], v135 offset0:96 offset1:97
	ds_read2_b32 v[96:97], v135 offset0:98 offset1:99
	ds_read2_b32 v[98:99], v135 offset0:104 offset1:105
	ds_read2_b32 v[100:101], v135 offset0:106 offset1:107
	s_mov_b64 s[14:15], 0
	s_waitcnt lgkmcnt(3)
	v_fma_f32 v106, v80, s40, v14
	v_fma_f32 v107, v81, s40, v15
	s_waitcnt lgkmcnt(2)
	v_fma_f32 v104, v82, s40, v96
	v_fma_f32 v105, v83, s40, v97
	ds_read2_b32 v[14:15], v135 offset0:112 offset1:113
	ds_read2_b32 v[96:97], v135 offset0:114 offset1:115
	ds_read2_b32 v[150:151], v135 offset0:120 offset1:121
	ds_read2_b32 v[152:153], v135 offset0:122 offset1:123
	s_waitcnt lgkmcnt(5)
	v_fma_f32 v102, v84, s40, v98
	v_fma_f32 v103, v85, s40, v99
	s_waitcnt lgkmcnt(4)
	v_fma_f32 v108, v86, s40, v100
	v_fma_f32 v109, v87, s40, v101
	s_waitcnt lgkmcnt(3)
	v_fma_f32 v98, v88, s40, v14
	v_fma_f32 v99, v89, s40, v15
	s_waitcnt lgkmcnt(2)
	v_fma_f32 v100, v90, s40, v96
	v_fma_f32 v101, v91, s40, v97
	s_waitcnt lgkmcnt(1)
	v_fma_f32 v96, v92, s40, v150
	v_fma_f32 v97, v93, s40, v151
	s_waitcnt lgkmcnt(0)
	v_fma_f32 v14, v94, s40, v152
	v_fma_f32 v15, v95, s40, v153
.LBB0_40:
	s_andn2_b64 vcc, exec, s[14:15]
	s_cbranch_vccnz .LBB0_17
	v_fma_f32 v106, v80, s40, v136
	v_fma_f32 v107, v81, s40, v137
	v_fma_f32 v104, v82, s40, v136
	v_fma_f32 v105, v83, s40, v137
	v_fma_f32 v102, v84, s40, v136
	v_fma_f32 v103, v85, s40, v137
	v_fma_f32 v108, v86, s40, v136
	v_fma_f32 v109, v87, s40, v137
	v_fma_f32 v98, v88, s40, v136
	v_fma_f32 v99, v89, s40, v137
	v_fma_f32 v100, v90, s40, v136
	v_fma_f32 v101, v91, s40, v137
	v_fma_f32 v96, v92, s40, v136
	v_fma_f32 v97, v93, s40, v137
	v_fma_f32 v14, v94, s40, v136
	v_fma_f32 v15, v95, s40, v137
	s_branch .LBB0_17

; template <int MODE>
; __device__ __forceinline__ void attn_item(LAS unsigned char* lds, const AttnArgs& a, const int tid) {
;     ...
;             constexpr int KD = AT_KD, VD = AT_VD;
;             bf16x8 kf[KD];
;     ...
; #pragma unroll
;             for (int i = 0; i < KD; ++i) kf[i] = AT_KLD(i);
; #pragma unroll
;             for (int i = 0; i < 2 * NKS; ++i) { s[i & 1] = MFMA32(kf[i % KD], qf[i >> 1], s[i & 1]); if (i + KD < 2 * NKS) kf[i % KD] = AT_KLD(i + KD); }
;     ...
;             bf16x8 vf[VD];
;     ...
; #pragma unroll
;             for (int j = 0; j < VD; ++j) AT_VLD(j);
;             const float sc = a.sc;
;             const bool diag = (MODE == 1) && (t * 64 + 63 > qw0);
;             const bool near = (MODE == 2) && (t >= tw - 2);
;             bf16x8 pf[2];
; #pragma unroll
;             for (int kt = 0; kt < 2; ++kt) {
;                 if (MODE == 1) {
;                     const LAS float* csb = (const LAS float*)(lds + A_CS) + t * 64 + 32 * kt + 4 * h;
;                     const int mb = t * 64 + 32 * kt + 4 * h - (qw0 + r);
; #pragma unroll
;                     for (int g = 0; g < 4; ++g) { const f32x4 cv = *(const LAS f32x4*)(csb + 8 * g);
; #pragma unroll
;                         for (int e = 0; e < 4; ++e) { float x = fmaf(s[kt][4 * g + e], sc, addc) + cv[e]; if (diag && (mb + 8 * g + e > 0)) x = -1e30f; s[kt][4 * g + e] = x; } }
;                 } else if (MODE == 2) {
;                     if (near) {
;                         const LAS float* lut = (const LAS float*)(lds + A_LUT) + (t * 64 + 32 * kt + 4 * h - (qw0 + r) + 191);
; #pragma unroll
;                         for (int i = 0; i < 16; ++i) s[kt][i] = fmaf(s[kt][i], sc, lut[8 * (i >> 2) + (i & 3)]);
;                     } else {
; #pragma unroll
;                         for (int i = 0; i < 16; ++i) s[kt][i] = fmaf(s[kt][i], sc, addc);
;                     }
;                 } else {
; #pragma unroll
;                     for (int i = 0; i < 16; ++i) s[kt][i] = fmaf(s[kt][i], sc, addc);
;                 }
;                 float ls = 0.f;
; #pragma unroll
;                 for (int i = 0; i < 16; ++i) { const float pv = fast_exp2(s[kt][i]); s[kt][i] = pv; ls += pv; }
;                 l += ls;
; #pragma unroll
;                 for (int ss = 0; ss < 2; ++ss) { u32x4 w;
;                     w.x = pk2(s[kt][8 * ss + 0], s[kt][8 * ss + 1]); w.y = pk2(s[kt][8 * ss + 2], s[kt][8 * ss + 3]);
.LBB0_61:
	s_cmp_gt_i32 s34, s55
	v_add_u32_e32 v227, s60, v225
	s_cbranch_scc1 .LBB0_63
	s_sub_i32 s28, s60, 64
	s_cmp_gt_i32 s28, s51
	s_cbranch_scc1 .Lmy_fox_diag1
	ds_read_b128 v[2:5], v198
	ds_read_b128 v[6:9], v198 offset:8192
	ds_read_b128 v[10:13], v199
	ds_read_b128 v[156:159], v199 offset:8192
	s_sub_i32 s28, s60, 64
	s_waitcnt lgkmcnt(3)
	v_mfma_f32_32x32x16_bf16 v[96:111], v[2:5], v[116:119], 0
	ds_read_b128 v[2:5], v200
	s_cmp_gt_i32 s28, s51
	v_add_u32_e32 v0, 0xffffff81, v227
	s_cselect_b64 s[28:29], -1, 0
	s_movk_i32 s35, 0xffef
	s_waitcnt lgkmcnt(3)
	v_mfma_f32_32x32x16_bf16 v[80:95], v[6:9], v[116:119], 0
	ds_read_b128 v[6:9], v200 offset:8192
	s_movk_i32 s61, 0xffee
	s_movk_i32 s62, 0xffed
	s_movk_i32 s63, 0xffe8
	s_movk_i32 s40, 0xffe7
	s_movk_i32 s81, 0xffe6
	s_movk_i32 s23, 0xffe5
	s_waitcnt lgkmcnt(3)
	v_mfma_f32_32x32x16_bf16 v[96:111], v[10:13], v[120:123], v[96:111]
	ds_read_b128 v[10:13], v201
	s_waitcnt lgkmcnt(3)
	v_mfma_f32_32x32x16_bf16 v[80:95], v[156:159], v[120:123], v[80:95]
	ds_read_b128 v[156:159], v201 offset:8192
	s_waitcnt lgkmcnt(3)
	v_mfma_f32_32x32x16_bf16 v[96:111], v[2:5], v[124:127], v[96:111]
	ds_read_b128 v[2:5], v213
	s_waitcnt lgkmcnt(3)
	v_mfma_f32_32x32x16_bf16 v[80:95], v[6:9], v[124:127], v[80:95]
	ds_read_b128 v[6:9], v213 offset:8192
	s_waitcnt lgkmcnt(3)
	v_mfma_f32_32x32x16_bf16 v[96:111], v[10:13], v[128:131], v[96:111]
	ds_read_b128 v[10:13], v214
	s_waitcnt lgkmcnt(3)
	v_mfma_f32_32x32x16_bf16 v[80:95], v[156:159], v[128:131], v[80:95]
	ds_read_b128 v[156:159], v214 offset:8192
	s_waitcnt lgkmcnt(3)
	v_mfma_f32_32x32x16_bf16 v[96:111], v[2:5], v[132:135], v[96:111]
	ds_read_b128 v[2:5], v215
	s_waitcnt lgkmcnt(3)
	v_mfma_f32_32x32x16_bf16 v[80:95], v[6:9], v[132:135], v[80:95]
	ds_read_b128 v[6:9], v215 offset:8192
	s_waitcnt lgkmcnt(3)
	v_mfma_f32_32x32x16_bf16 v[96:111], v[10:13], v[136:139], v[96:111]
	ds_read_b128 v[10:13], v216
	s_waitcnt lgkmcnt(3)
	v_mfma_f32_32x32x16_bf16 v[80:95], v[156:159], v[136:139], v[80:95]
	ds_read_b128 v[156:159], v216 offset:8192
	s_waitcnt lgkmcnt(3)
	v_mfma_f32_32x32x16_bf16 v[96:111], v[2:5], v[140:143], v[96:111]
	s_waitcnt lgkmcnt(2)
	v_mfma_f32_32x32x16_bf16 v[80:95], v[6:9], v[140:143], v[80:95]
	s_waitcnt lgkmcnt(1)
	v_mfma_f32_32x32x16_bf16 v[96:111], v[10:13], v[144:147], v[96:111]
	ds_read_b64_tr_b16 v[6:7], v217 offset:16384
	ds_read_b64_tr_b16 v[8:9], v218 offset:16384
	ds_read_b64_tr_b16 v[10:11], v219 offset:16384
	ds_read_b64_tr_b16 v[12:13], v220 offset:16384
	ds_read_b64_tr_b16 v[2:3], v221 offset:16384
	ds_read_b64_tr_b16 v[4:5], v222 offset:16384
	s_nop 5
	v_fmamk_f32 v14, v96, 0x3e0293ee, v151
	s_waitcnt lgkmcnt(6)
	v_mfma_f32_32x32x16_bf16 v[80:95], v[156:159], v[144:147], v[80:95]
	ds_read_b128 v[156:159], v226
	ds_read_b128 v[160:163], v226 offset:32
	v_fmamk_f32 v15, v97, 0x3e0293ee, v151
	v_fmamk_f32 v96, v98, 0x3e0293ee, v151
	s_waitcnt lgkmcnt(1)
	v_add_f32_e32 v14, v14, v156
	v_add_f32_e32 v15, v15, v157
	v_add_f32_e32 v96, v96, v158
	v_mov_b32_e32 v155, v96
	v_fmamk_f32 v96, v99, 0x3e0293ee, v151
	v_add_f32_e32 v96, v96, v159
	v_mov_b32_e32 v156, v96
	v_fmamk_f32 v96, v100, 0x3e0293ee, v151
	s_waitcnt lgkmcnt(0)
	v_add_f32_e32 v96, v96, v160
	v_mov_b32_e32 v157, v96
	v_fmamk_f32 v96, v101, 0x3e0293ee, v151
	v_add_f32_e32 v96, v96, v161
	v_mov_b32_e32 v101, v96
	v_fmamk_f32 v96, v102, 0x3e0293ee, v151
	v_add_f32_e32 v96, v96, v162
	v_mov_b32_e32 v158, v96
	v_fmamk_f32 v96, v103, 0x3e0293ee, v151
	v_add_f32_e32 v96, v96, v163
	v_mov_b32_e32 v103, v96
	ds_read_b128 v[96:99], v226 offset:64
	v_fmamk_f32 v100, v104, 0x3e0293ee, v151
	v_exp_f32_e32 v14, v14
	s_waitcnt lgkmcnt(0)
	v_add_f32_e32 v96, v100, v96
	v_mov_b32_e32 v159, v96
	v_fmamk_f32 v96, v105, 0x3e0293ee, v151
	v_add_f32_e32 v96, v96, v97
	v_mov_b32_e32 v105, v96
	v_fmamk_f32 v96, v106, 0x3e0293ee, v151
	v_add_f32_e32 v96, v96, v98
	v_mov_b32_e32 v161, v96
	v_fmamk_f32 v96, v107, 0x3e0293ee, v151
	v_add_f32_e32 v96, v96, v99
	v_mov_b32_e32 v107, v96
	ds_read_b128 v[96:99], v226 offset:96
	v_fmamk_f32 v100, v108, 0x3e0293ee, v151
	v_exp_f32_e32 v104, v155
	s_waitcnt lgkmcnt(0)
	v_add_f32_e32 v96, v100, v96
	v_fmamk_f32 v100, v109, 0x3e0293ee, v151
	v_add_f32_e32 v97, v100, v97
	v_fmamk_f32 v100, v110, 0x3e0293ee, v151
	v_add_f32_e32 v98, v100, v98
	v_fmamk_f32 v100, v111, 0x3e0293ee, v151
	v_add_f32_e32 v99, v100, v99
	v_exp_f32_e32 v100, v15
	v_exp_f32_e32 v102, v156
	v_exp_f32_e32 v106, v157
	v_exp_f32_e32 v108, v101
	v_exp_f32_e32 v156, v158
	v_exp_f32_e32 v110, v103
	v_exp_f32_e32 v168, v96
	v_exp_f32_e32 v166, v97
	v_exp_f32_e32 v172, v98
	v_exp_f32_e32 v170, v99
	v_cvt_pk_bf16_f32 v96, v14, v100
	v_cvt_pk_bf16_f32 v97, v104, v102
	v_cvt_pk_bf16_f32 v98, v106, v108
	v_cvt_pk_bf16_f32 v99, v156, v110
	v_exp_f32_e32 v160, v159
	v_exp_f32_e32 v158, v105
	v_mfma_f32_32x32x16_bf16 v[64:79], v[6:9], v[96:99], v[64:79]
	ds_read_b64_tr_b16 v[6:7], v223 offset:16384
	ds_read_b64_tr_b16 v[8:9], v224 offset:16384
	v_exp_f32_e32 v164, v161
	v_exp_f32_e32 v162, v107
	v_cvt_pk_bf16_f32 v232, v160, v158
	v_cvt_pk_bf16_f32 v234, v168, v166
	v_cvt_pk_bf16_f32 v235, v172, v170
	v_cvt_pk_bf16_f32 v233, v164, v162
	v_mfma_f32_32x32x16_bf16 v[48:63], v[10:13], v[96:99], v[48:63]
	ds_read_b64_tr_b16 v[10:11], v217 offset:20480
	ds_read_b64_tr_b16 v[12:13], v218 offset:20480
	v_add_f32_e32 v0, 0, v14
	v_fmamk_f32 v15, v88, 0x3e0293ee, v151
	v_mfma_f32_32x32x16_bf16 v[32:47], v[2:5], v[96:99], v[32:47]
	ds_read_b64_tr_b16 v[2:3], v219 offset:20480
	ds_read_b64_tr_b16 v[4:5], v220 offset:20480
	s_waitcnt lgkmcnt(4)
; #define LAS __attribute__((address_space(3)))
; #define MFMA32(a, b, c) __builtin_amdgcn_mfma_f32_32x32x16_bf16((a), (b), (c), 0, 0, 0)
; __device__ __forceinline__ float fast_exp2(float x) { return __builtin_amdgcn_exp2f(x); }
; template <int MODE>
; __device__ __forceinline__ void attn_item(LAS unsigned char* lds, const AttnArgs& a, const int tid) {
;     ...
;             for (int kt = 0; kt < 2; ++kt) {
;                 if (MODE == 1) {
;                     const LAS float* csb = (const LAS float*)(lds + A_CS) + t * 64 + 32 * kt + 4 * h;
;                     const int mb = t * 64 + 32 * kt + 4 * h - (qw0 + r);
; #pragma unroll
;                     for (int g = 0; g < 4; ++g) { const f32x4 cv = *(const LAS f32x4*)(csb + 8 * g);
; #pragma unroll
;                         for (int e = 0; e < 4; ++e) { float x = fmaf(s[kt][4 * g + e], sc, addc) + cv[e]; if (diag && (mb + 8 * g + e > 0)) x = -1e30f; s[kt][4 * g + e] = x; } }
;                 } else if (MODE == 2) {
;                     if (near) {
;                         const LAS float* lut = (const LAS float*)(lds + A_LUT) + (t * 64 + 32 * kt + 4 * h - (qw0 + r) + 191);
; #pragma unroll
;                         for (int i = 0; i < 16; ++i) s[kt][i] = fmaf(s[kt][i], sc, lut[8 * (i >> 2) + (i & 3)]);
;                     } else {
; #pragma unroll
;                         for (int i = 0; i < 16; ++i) s[kt][i] = fmaf(s[kt][i], sc, addc);
;                     }
;                 } else {
; #pragma unroll
;                     for (int i = 0; i < 16; ++i) s[kt][i] = fmaf(s[kt][i], sc, addc);
;                 }
;                 float ls = 0.f;
; #pragma unroll
;                 for (int i = 0; i < 16; ++i) { const float pv = fast_exp2(s[kt][i]); s[kt][i] = pv; ls += pv; }
;                 l += ls;
; #pragma unroll
;                 for (int ss = 0; ss < 2; ++ss) { u32x4 w;
;                     w.x = pk2(s[kt][8 * ss + 0], s[kt][8 * ss + 1]); w.y = pk2(s[kt][8 * ss + 2], s[kt][8 * ss + 3]);
;                     w.z = pk2(s[kt][8 * ss + 4], s[kt][8 * ss + 5]); w.w = pk2(s[kt][8 * ss + 6], s[kt][8 * ss + 7]);
;                     pf[ss] = __builtin_bit_cast(bf16x8, w); }
; #pragma unroll
;                 for (int jj = 0; jj < 8; ++jj) { const int j = 8 * kt + jj;
;                     o[jj & 3] = MFMA32(vf[j % VD], pf[jj >> 2], o[jj & 3]);
;                     if (j + VD < 16) AT_VLD(j + VD); }
	v_mfma_f32_32x32x16_bf16 v[16:31], v[6:9], v[96:99], v[16:31]
	ds_read_b64_tr_b16 v[6:7], v221 offset:20480
	ds_read_b64_tr_b16 v[8:9], v222 offset:20480
	s_waitcnt lgkmcnt(4)
	v_mfma_f32_32x32x16_bf16 v[64:79], v[10:13], v[232:235], v[64:79]
	ds_read_b64_tr_b16 v[10:11], v223 offset:20480
	ds_read_b64_tr_b16 v[12:13], v224 offset:20480
	ds_read_b64_tr_b16 v[236:237], v217 offset:24576
	ds_read_b64_tr_b16 v[238:239], v218 offset:24576
	ds_read_b64_tr_b16 v[240:241], v219 offset:24576
	ds_read_b64_tr_b16 v[242:243], v220 offset:24576
	ds_read_b64_tr_b16 v[96:97], v221 offset:24576
	ds_read_b64_tr_b16 v[98:99], v222 offset:24576
	s_waitcnt lgkmcnt(10)
	v_mfma_f32_32x32x16_bf16 v[48:63], v[2:5], v[232:235], v[48:63]
	ds_read_b128 v[2:5], v226 offset:128
	s_waitcnt lgkmcnt(9)
	v_mfma_f32_32x32x16_bf16 v[32:47], v[6:9], v[232:235], v[32:47]
	v_add_u32_e32 v6, 0xffffffa1, v227
	v_fmamk_f32 v7, v80, 0x3e0293ee, v151
	s_waitcnt lgkmcnt(0)
	v_add_f32_e32 v2, v7, v2
	v_mov_b32_e32 v7, v2
	v_fmamk_f32 v2, v81, 0x3e0293ee, v151
	v_add_f32_e32 v2, v2, v3
	v_mov_b32_e32 v8, v2
	v_fmamk_f32 v2, v82, 0x3e0293ee, v151
	v_add_f32_e32 v2, v2, v4
	v_mov_b32_e32 v9, v2
	v_fmamk_f32 v2, v83, 0x3e0293ee, v151
	v_add_f32_e32 v2, v2, v5
	v_mfma_f32_32x32x16_bf16 v[16:31], v[10:13], v[232:235], v[16:31]
	v_mov_b32_e32 v10, v2
	ds_read_b128 v[2:5], v226 offset:160
	v_fmamk_f32 v11, v84, 0x3e0293ee, v151
	v_fmamk_f32 v83, v92, 0x3e0293ee, v151
	s_waitcnt lgkmcnt(0)
	v_add_f32_e32 v2, v11, v2
	v_mov_b32_e32 v11, v2
	v_fmamk_f32 v2, v85, 0x3e0293ee, v151
	v_add_f32_e32 v2, v2, v3
	v_mov_b32_e32 v12, v2
	v_fmamk_f32 v2, v86, 0x3e0293ee, v151
	v_add_f32_e32 v2, v2, v4
	v_mov_b32_e32 v13, v2
	v_fmamk_f32 v2, v87, 0x3e0293ee, v151
	v_add_f32_e32 v2, v2, v5
	v_mov_b32_e32 v14, v2
	ds_read_b128 v[2:5], v226 offset:192
	v_exp_f32_e32 v101, v7
	v_exp_f32_e32 v105, v8
	s_waitcnt lgkmcnt(0)
	v_add_f32_e32 v2, v15, v2
	v_mov_b32_e32 v15, v2
	v_fmamk_f32 v2, v89, 0x3e0293ee, v151
	v_add_f32_e32 v2, v2, v3
	v_mov_b32_e32 v80, v2
	v_fmamk_f32 v2, v90, 0x3e0293ee, v151
	v_add_f32_e32 v2, v2, v4
	v_mov_b32_e32 v81, v2
	v_fmamk_f32 v2, v91, 0x3e0293ee, v151
	v_add_f32_e32 v2, v2, v5
	v_mov_b32_e32 v82, v2
	ds_read_b128 v[2:5], v226 offset:224
	v_exp_f32_e32 v103, v9
	v_exp_f32_e32 v107, v10
	s_waitcnt lgkmcnt(0)
	v_add_f32_e32 v2, v83, v2
	v_mov_b32_e32 v83, v2
	v_fmamk_f32 v2, v93, 0x3e0293ee, v151
	v_add_f32_e32 v2, v2, v3
	v_mov_b32_e32 v84, v2
	v_fmamk_f32 v2, v94, 0x3e0293ee, v151
	v_add_f32_e32 v2, v2, v4
	v_mov_b32_e32 v4, v2
	v_fmamk_f32 v2, v95, 0x3e0293ee, v151
	v_add_f32_e32 v2, v2, v5
	v_mov_b32_e32 v5, v2
	v_add_f32_e32 v2, v100, v0
	v_add_f32_e32 v3, v101, v1
	v_exp_f32_e32 v109, v11
	v_add_f32_e32 v2, v104, v2
	v_add_f32_e32 v3, v105, v3
	v_exp_f32_e32 v157, v12
	v_add_f32_e32 v2, v102, v2
	v_add_f32_e32 v3, v103, v3
	v_exp_f32_e32 v111, v13
	v_add_f32_e32 v2, v106, v2
	v_add_f32_e32 v3, v107, v3
	v_exp_f32_e32 v161, v14
	ds_read_b64_tr_b16 v[10:11], v223 offset:24576
	ds_read_b64_tr_b16 v[12:13], v224 offset:24576
	v_exp_f32_e32 v159, v15
	v_add_f32_e32 v2, v108, v2
	v_add_f32_e32 v3, v109, v3
	v_exp_f32_e32 v165, v80
	v_add_f32_e32 v2, v156, v2
	v_add_f32_e32 v3, v157, v3
	v_exp_f32_e32 v163, v81
	v_add_f32_e32 v2, v110, v2
	v_add_f32_e32 v3, v111, v3
	v_exp_f32_e32 v169, v82
	v_add_f32_e32 v2, v160, v2
	v_add_f32_e32 v3, v161, v3
	v_cvt_pk_bf16_f32 v6, v101, v105
	v_cvt_pk_bf16_f32 v7, v103, v107
	v_cvt_pk_bf16_f32 v8, v109, v157
	v_cvt_pk_bf16_f32 v9, v111, v161
	v_exp_f32_e32 v167, v83
	v_add_f32_e32 v2, v158, v2
	v_add_f32_e32 v3, v159, v3
	v_mfma_f32_32x32x16_bf16 v[64:79], v[236:239], v[6:9], v[64:79]
	v_exp_f32_e32 v173, v84
	v_add_f32_e32 v2, v164, v2
	v_add_f32_e32 v3, v165, v3
	v_exp_f32_e32 v171, v4
	v_add_f32_e32 v2, v162, v2
	v_add_f32_e32 v3, v163, v3
	v_exp_f32_e32 v155, v5
	v_add_f32_e32 v2, v168, v2
	v_add_f32_e32 v3, v169, v3
	ds_read_b64_tr_b16 v[84:85], v217 offset:28672
	ds_read_b64_tr_b16 v[86:87], v218 offset:28672
	v_mfma_f32_32x32x16_bf16 v[48:63], v[240:243], v[6:9], v[48:63]
	ds_read_b64_tr_b16 v[80:81], v219 offset:28672
	ds_read_b64_tr_b16 v[82:83], v220 offset:28672
	v_add_f32_e64 v2, v166, v2
	v_add_f32_e64 v3, v167, v3
	v_cvt_pk_bf16_f32 v4, v167, v173
	v_add_f32_e32 v2, v172, v2
	v_add_f32_e32 v3, v173, v3
	v_cvt_pk_bf16_f32 v5, v171, v155
	v_add_f32_e32 v2, v170, v2
	v_add_f32_e32 v3, v171, v3
	v_mfma_f32_32x32x16_bf16 v[32:47], v[96:99], v[6:9], v[32:47]
	v_add_f32_e64 v14, v154, v2
	v_add_f32_e64 v15, v155, v3
	v_cvt_pk_bf16_f32 v2, v159, v165
	v_cvt_pk_bf16_f32 v3, v163, v169
	v_add_f32_e32 v154, v14, v15
	s_waitcnt lgkmcnt(4)
	v_mfma_f32_32x32x16_bf16 v[16:31], v[10:13], v[6:9], v[16:31]
	ds_read_b64_tr_b16 v[6:7], v221 offset:28672
	ds_read_b64_tr_b16 v[8:9], v222 offset:28672
	ds_read_b64_tr_b16 v[10:11], v223 offset:28672
	ds_read_b64_tr_b16 v[12:13], v224 offset:28672
	s_waitcnt lgkmcnt(6)
	v_mfma_f32_32x32x16_bf16 v[64:79], v[84:87], v[2:5], v[64:79]
	s_waitcnt lgkmcnt(4)
	v_mfma_f32_32x32x16_bf16 v[48:63], v[80:83], v[2:5], v[48:63]
	s_waitcnt lgkmcnt(2)
	v_mfma_f32_32x32x16_bf16 v[32:47], v[6:9], v[2:5], v[32:47]
	s_waitcnt lgkmcnt(0)
	v_mfma_f32_32x32x16_bf16 v[16:31], v[10:13], v[2:5], v[16:31]
	s_branch .LBB0_63
; #define LAS __attribute__((address_space(3)))
; #define MFMA32(a, b, c) __builtin_amdgcn_mfma_f32_32x32x16_bf16((a), (b), (c), 0, 0, 0)
; template <int MODE>
; __device__ __forceinline__ void attn_item(LAS unsigned char* lds, const AttnArgs& a, const int tid) {
;     ...
;             constexpr int KD = AT_KD, VD = AT_VD;
;             bf16x8 kf[KD];
;     ...
; #pragma unroll
;             for (int i = 0; i < KD; ++i) kf[i] = AT_KLD(i);
; #pragma unroll
;             for (int i = 0; i < 2 * NKS; ++i) { s[i & 1] = MFMA32(kf[i % KD], qf[i >> 1], s[i & 1]); if (i + KD < 2 * NKS) kf[i % KD] = AT_KLD(i + KD); }
;     ...
;             bf16x8 vf[VD];
;     ...
; #pragma unroll
;             for (int j = 0; j < VD; ++j) AT_VLD(j);
;             const float sc = a.sc;
;             const bool diag = (MODE == 1) && (t * 64 + 63 > qw0);
;             const bool near = (MODE == 2) && (t >= tw - 2);
;             bf16x8 pf[2];
; #pragma unroll
;             for (int kt = 0; kt < 2; ++kt) {
;                 if (MODE == 1) {
;                     const LAS float* csb = (const LAS float*)(lds + A_CS) + t * 64 + 32 * kt + 4 * h;
;                     const int mb = t * 64 + 32 * kt + 4 * h - (qw0 + r);
; #pragma unroll
;                     for (int g = 0; g < 4; ++g) { const f32x4 cv = *(const LAS f32x4*)(csb + 8 * g);
; #pragma unroll
;                         for (int e = 0; e < 4; ++e) { float x = fmaf(s[kt][4 * g + e], sc, addc) + cv[e]; if (diag && (mb + 8 * g + e > 0)) x = -1e30f; s[kt][4 * g + e] = x; } }
.Lmy_fox_diag1:
	ds_read_b128 v[2:5], v198
	ds_read_b128 v[6:9], v198 offset:8192
	ds_read_b128 v[10:13], v199
	ds_read_b128 v[156:159], v199 offset:8192
	s_sub_i32 s28, s60, 64
	s_waitcnt lgkmcnt(3)
	v_mfma_f32_32x32x16_bf16 v[96:111], v[2:5], v[116:119], 0
	ds_read_b128 v[2:5], v200
	s_cmp_gt_i32 s28, s51
	v_add_u32_e32 v0, 0xffffff81, v227
	s_cselect_b64 s[28:29], -1, 0
	v_cmp_lt_i32_e32 vcc, 0, v0
	s_and_b64 vcc, s[28:29], vcc
	s_movk_i32 s35, 0xffef
	s_waitcnt lgkmcnt(3)
	v_mfma_f32_32x32x16_bf16 v[80:95], v[6:9], v[116:119], 0
	ds_read_b128 v[6:9], v200 offset:8192
	s_movk_i32 s61, 0xffee
	s_movk_i32 s62, 0xffed
	s_movk_i32 s63, 0xffe8
	s_movk_i32 s40, 0xffe7
	s_movk_i32 s81, 0xffe6
	s_movk_i32 s23, 0xffe5
	s_waitcnt lgkmcnt(3)
	v_mfma_f32_32x32x16_bf16 v[96:111], v[10:13], v[120:123], v[96:111]
	ds_read_b128 v[10:13], v201
	s_waitcnt lgkmcnt(3)
	v_mfma_f32_32x32x16_bf16 v[80:95], v[156:159], v[120:123], v[80:95]
	ds_read_b128 v[156:159], v201 offset:8192
	s_waitcnt lgkmcnt(3)
	v_mfma_f32_32x32x16_bf16 v[96:111], v[2:5], v[124:127], v[96:111]
	ds_read_b128 v[2:5], v213
	s_waitcnt lgkmcnt(3)
	v_mfma_f32_32x32x16_bf16 v[80:95], v[6:9], v[124:127], v[80:95]
	ds_read_b128 v[6:9], v213 offset:8192
	s_waitcnt lgkmcnt(3)
	v_mfma_f32_32x32x16_bf16 v[96:111], v[10:13], v[128:131], v[96:111]
	ds_read_b128 v[10:13], v214
	s_waitcnt lgkmcnt(3)
	v_mfma_f32_32x32x16_bf16 v[80:95], v[156:159], v[128:131], v[80:95]
	ds_read_b128 v[156:159], v214 offset:8192
	s_waitcnt lgkmcnt(3)
	v_mfma_f32_32x32x16_bf16 v[96:111], v[2:5], v[132:135], v[96:111]
	ds_read_b128 v[2:5], v215
	s_waitcnt lgkmcnt(3)
	v_mfma_f32_32x32x16_bf16 v[80:95], v[6:9], v[132:135], v[80:95]
	ds_read_b128 v[6:9], v215 offset:8192
	s_waitcnt lgkmcnt(3)
	v_mfma_f32_32x32x16_bf16 v[96:111], v[10:13], v[136:139], v[96:111]
	ds_read_b128 v[10:13], v216
	s_waitcnt lgkmcnt(3)
	v_mfma_f32_32x32x16_bf16 v[80:95], v[156:159], v[136:139], v[80:95]
	ds_read_b128 v[156:159], v216 offset:8192
	s_waitcnt lgkmcnt(3)
	v_mfma_f32_32x32x16_bf16 v[96:111], v[2:5], v[140:143], v[96:111]
	s_waitcnt lgkmcnt(2)
	v_mfma_f32_32x32x16_bf16 v[80:95], v[6:9], v[140:143], v[80:95]
	s_waitcnt lgkmcnt(1)
	v_mfma_f32_32x32x16_bf16 v[96:111], v[10:13], v[144:147], v[96:111]
	ds_read_b64_tr_b16 v[6:7], v217 offset:16384
	ds_read_b64_tr_b16 v[8:9], v218 offset:16384
	ds_read_b64_tr_b16 v[10:11], v219 offset:16384
	ds_read_b64_tr_b16 v[12:13], v220 offset:16384
	ds_read_b64_tr_b16 v[2:3], v221 offset:16384
	ds_read_b64_tr_b16 v[4:5], v222 offset:16384
	s_nop 5
	v_fmamk_f32 v14, v96, 0x3e0293ee, v151
	s_waitcnt lgkmcnt(6)
	v_mfma_f32_32x32x16_bf16 v[80:95], v[156:159], v[144:147], v[80:95]
	ds_read_b128 v[156:159], v226
	ds_read_b128 v[160:163], v226 offset:32
	v_fmamk_f32 v15, v97, 0x3e0293ee, v151
	v_fmamk_f32 v96, v98, 0x3e0293ee, v151
	s_waitcnt lgkmcnt(1)
	v_add_f32_e32 v14, v14, v156
	v_cndmask_b32_e32 v14, v14, v210, vcc
	v_cmp_lt_i32_e32 vcc, -1, v0
	v_add_f32_e32 v15, v15, v157
	s_and_b64 vcc, s[28:29], vcc
	v_cndmask_b32_e32 v15, v15, v210, vcc
	v_cmp_lt_i32_e32 vcc, -2, v0
	v_add_f32_e32 v96, v96, v158
	s_and_b64 vcc, s[28:29], vcc
	v_cndmask_b32_e32 v155, v96, v210, vcc
	v_fmamk_f32 v96, v99, 0x3e0293ee, v151
	v_cmp_lt_i32_e32 vcc, -3, v0
	v_add_f32_e32 v96, v96, v159
	s_and_b64 vcc, s[28:29], vcc
	v_cndmask_b32_e32 v156, v96, v210, vcc
	v_fmamk_f32 v96, v100, 0x3e0293ee, v151
	v_cmp_lt_i32_e32 vcc, -8, v0
	s_waitcnt lgkmcnt(0)
	v_add_f32_e32 v96, v96, v160
	s_and_b64 vcc, s[28:29], vcc
	v_cndmask_b32_e32 v157, v96, v210, vcc
	v_fmamk_f32 v96, v101, 0x3e0293ee, v151
	v_cmp_lt_i32_e32 vcc, -9, v0
	v_add_f32_e32 v96, v96, v161
	s_and_b64 vcc, s[28:29], vcc
	v_cndmask_b32_e32 v101, v96, v210, vcc
	v_fmamk_f32 v96, v102, 0x3e0293ee, v151
	v_cmp_lt_i32_e32 vcc, -10, v0
	v_add_f32_e32 v96, v96, v162
	s_and_b64 vcc, s[28:29], vcc
	v_cndmask_b32_e32 v158, v96, v210, vcc
	v_fmamk_f32 v96, v103, 0x3e0293ee, v151
	v_cmp_lt_i32_e32 vcc, -11, v0
	v_add_f32_e32 v96, v96, v163
	s_and_b64 vcc, s[28:29], vcc
	v_cndmask_b32_e32 v103, v96, v210, vcc
	ds_read_b128 v[96:99], v226 offset:64
	v_fmamk_f32 v100, v104, 0x3e0293ee, v151
	v_cmp_lt_i32_e32 vcc, -16, v0
	s_and_b64 vcc, s[28:29], vcc
	v_exp_f32_e32 v14, v14
	s_waitcnt lgkmcnt(0)
	v_add_f32_e32 v96, v100, v96
	v_cndmask_b32_e32 v159, v96, v210, vcc
	v_fmamk_f32 v96, v105, 0x3e0293ee, v151
	v_cmp_lt_i32_e32 vcc, s35, v0
	v_add_f32_e32 v96, v96, v97
	s_and_b64 vcc, s[28:29], vcc
	v_cndmask_b32_e32 v105, v96, v210, vcc
	v_fmamk_f32 v96, v106, 0x3e0293ee, v151
	v_cmp_lt_i32_e32 vcc, s61, v0
	v_add_f32_e32 v96, v96, v98
	s_and_b64 vcc, s[28:29], vcc
	v_cndmask_b32_e32 v161, v96, v210, vcc
	v_fmamk_f32 v96, v107, 0x3e0293ee, v151
	v_cmp_lt_i32_e32 vcc, s62, v0
	v_add_f32_e32 v96, v96, v99
	s_and_b64 vcc, s[28:29], vcc
	v_cndmask_b32_e32 v107, v96, v210, vcc
	ds_read_b128 v[96:99], v226 offset:96
	v_fmamk_f32 v100, v108, 0x3e0293ee, v151
	v_cmp_lt_i32_e32 vcc, s63, v0
	s_and_b64 vcc, s[28:29], vcc
	v_exp_f32_e32 v104, v155
	s_waitcnt lgkmcnt(0)
; #define LAS __attribute__((address_space(3)))
; #define MFMA32(a, b, c) __builtin_amdgcn_mfma_f32_32x32x16_bf16((a), (b), (c), 0, 0, 0)
; __device__ __forceinline__ float fast_exp2(float x) { return __builtin_amdgcn_exp2f(x); }
; template <int MODE>
; __device__ __forceinline__ void attn_item(LAS unsigned char* lds, const AttnArgs& a, const int tid) {
;     ...
;             for (int kt = 0; kt < 2; ++kt) {
;                 if (MODE == 1) {
;                     const LAS float* csb = (const LAS float*)(lds + A_CS) + t * 64 + 32 * kt + 4 * h;
;                     const int mb = t * 64 + 32 * kt + 4 * h - (qw0 + r);
; #pragma unroll
;                     for (int g = 0; g < 4; ++g) { const f32x4 cv = *(const LAS f32x4*)(csb + 8 * g);
; #pragma unroll
;                         for (int e = 0; e < 4; ++e) { float x = fmaf(s[kt][4 * g + e], sc, addc) + cv[e]; if (diag && (mb + 8 * g + e > 0)) x = -1e30f; s[kt][4 * g + e] = x; } }
;                 } else if (MODE == 2) {
;                     if (near) {
;                         const LAS float* lut = (const LAS float*)(lds + A_LUT) + (t * 64 + 32 * kt + 4 * h - (qw0 + r) + 191);
; #pragma unroll
;                         for (int i = 0; i < 16; ++i) s[kt][i] = fmaf(s[kt][i], sc, lut[8 * (i >> 2) + (i & 3)]);
;                     } else {
; #pragma unroll
;                         for (int i = 0; i < 16; ++i) s[kt][i] = fmaf(s[kt][i], sc, addc);
;                     }
;                 } else {
; #pragma unroll
;                     for (int i = 0; i < 16; ++i) s[kt][i] = fmaf(s[kt][i], sc, addc);
;                 }
;                 float ls = 0.f;
; #pragma unroll
;                 for (int i = 0; i < 16; ++i) { const float pv = fast_exp2(s[kt][i]); s[kt][i] = pv; ls += pv; }
;                 l += ls;
; #pragma unroll
;                 for (int ss = 0; ss < 2; ++ss) { u32x4 w;
;                     w.x = pk2(s[kt][8 * ss + 0], s[kt][8 * ss + 1]); w.y = pk2(s[kt][8 * ss + 2], s[kt][8 * ss + 3]);
;                     w.z = pk2(s[kt][8 * ss + 4], s[kt][8 * ss + 5]); w.w = pk2(s[kt][8 * ss + 6], s[kt][8 * ss + 7]);
;                     pf[ss] = __builtin_bit_cast(bf16x8, w); }
; #pragma unroll
;                 for (int jj = 0; jj < 8; ++jj) { const int j = 8 * kt + jj;
;                     o[jj & 3] = MFMA32(vf[j % VD], pf[jj >> 2], o[jj & 3]);
;                     if (j + VD < 16) AT_VLD(j + VD); }
	v_add_f32_e32 v96, v100, v96
	v_cndmask_b32_e32 v96, v96, v210, vcc
	v_fmamk_f32 v100, v109, 0x3e0293ee, v151
	v_cmp_lt_i32_e32 vcc, s40, v0
	v_add_f32_e32 v97, v100, v97
	s_and_b64 vcc, s[28:29], vcc
	v_fmamk_f32 v100, v110, 0x3e0293ee, v151
	v_cndmask_b32_e32 v97, v97, v210, vcc
	v_add_f32_e32 v98, v100, v98
	v_cmp_lt_i32_e32 vcc, s81, v0
	v_fmamk_f32 v100, v111, 0x3e0293ee, v151
	s_and_b64 vcc, s[28:29], vcc
	v_add_f32_e32 v99, v100, v99
	v_exp_f32_e32 v100, v15
	v_exp_f32_e32 v102, v156
	v_exp_f32_e32 v106, v157
	v_exp_f32_e32 v108, v101
	v_exp_f32_e32 v156, v158
	v_exp_f32_e32 v110, v103
	v_cndmask_b32_e32 v98, v98, v210, vcc
	v_cmp_lt_i32_e32 vcc, s23, v0
	s_and_b64 vcc, s[28:29], vcc
	v_exp_f32_e32 v168, v96
	v_cndmask_b32_e32 v99, v99, v210, vcc
	v_exp_f32_e32 v166, v97
	v_exp_f32_e32 v172, v98
	v_exp_f32_e32 v170, v99
	v_cvt_pk_bf16_f32 v96, v14, v100
	v_cvt_pk_bf16_f32 v97, v104, v102
	v_cvt_pk_bf16_f32 v98, v106, v108
	v_cvt_pk_bf16_f32 v99, v156, v110
	v_exp_f32_e32 v160, v159
	v_exp_f32_e32 v158, v105
	v_mfma_f32_32x32x16_bf16 v[64:79], v[6:9], v[96:99], v[64:79]
	ds_read_b64_tr_b16 v[6:7], v223 offset:16384
	ds_read_b64_tr_b16 v[8:9], v224 offset:16384
	v_exp_f32_e32 v164, v161
	v_exp_f32_e32 v162, v107
	v_cvt_pk_bf16_f32 v232, v160, v158
	v_cvt_pk_bf16_f32 v234, v168, v166
	v_cvt_pk_bf16_f32 v235, v172, v170
	v_cvt_pk_bf16_f32 v233, v164, v162
	v_mfma_f32_32x32x16_bf16 v[48:63], v[10:13], v[96:99], v[48:63]
	ds_read_b64_tr_b16 v[10:11], v217 offset:20480
	ds_read_b64_tr_b16 v[12:13], v218 offset:20480
	v_add_f32_e32 v0, 0, v14
	v_fmamk_f32 v15, v88, 0x3e0293ee, v151
	v_mfma_f32_32x32x16_bf16 v[32:47], v[2:5], v[96:99], v[32:47]
	ds_read_b64_tr_b16 v[2:3], v219 offset:20480
	ds_read_b64_tr_b16 v[4:5], v220 offset:20480
	s_waitcnt lgkmcnt(4)
	v_mfma_f32_32x32x16_bf16 v[16:31], v[6:9], v[96:99], v[16:31]
	ds_read_b64_tr_b16 v[6:7], v221 offset:20480
	ds_read_b64_tr_b16 v[8:9], v222 offset:20480
	s_waitcnt lgkmcnt(4)
	v_mfma_f32_32x32x16_bf16 v[64:79], v[10:13], v[232:235], v[64:79]
	ds_read_b64_tr_b16 v[10:11], v223 offset:20480
	ds_read_b64_tr_b16 v[12:13], v224 offset:20480
	ds_read_b64_tr_b16 v[236:237], v217 offset:24576
	ds_read_b64_tr_b16 v[238:239], v218 offset:24576
	ds_read_b64_tr_b16 v[240:241], v219 offset:24576
	ds_read_b64_tr_b16 v[242:243], v220 offset:24576
	ds_read_b64_tr_b16 v[96:97], v221 offset:24576
	ds_read_b64_tr_b16 v[98:99], v222 offset:24576
	s_waitcnt lgkmcnt(10)
	v_mfma_f32_32x32x16_bf16 v[48:63], v[2:5], v[232:235], v[48:63]
	ds_read_b128 v[2:5], v226 offset:128
	s_waitcnt lgkmcnt(9)
	v_mfma_f32_32x32x16_bf16 v[32:47], v[6:9], v[232:235], v[32:47]
	v_add_u32_e32 v6, 0xffffffa1, v227
	v_fmamk_f32 v7, v80, 0x3e0293ee, v151
	v_cmp_lt_i32_e32 vcc, 0, v6
	s_waitcnt lgkmcnt(0)
	v_add_f32_e32 v2, v7, v2
	s_and_b64 vcc, s[28:29], vcc
	v_cndmask_b32_e32 v7, v2, v210, vcc
	v_fmamk_f32 v2, v81, 0x3e0293ee, v151
	v_cmp_lt_i32_e32 vcc, -1, v6
	v_add_f32_e32 v2, v2, v3
	s_and_b64 vcc, s[28:29], vcc
	v_cndmask_b32_e32 v8, v2, v210, vcc
	v_fmamk_f32 v2, v82, 0x3e0293ee, v151
	v_cmp_lt_i32_e32 vcc, -2, v6
	v_add_f32_e32 v2, v2, v4
	s_and_b64 vcc, s[28:29], vcc
	v_cndmask_b32_e32 v9, v2, v210, vcc
	v_fmamk_f32 v2, v83, 0x3e0293ee, v151
	v_cmp_lt_i32_e32 vcc, -3, v6
	v_add_f32_e32 v2, v2, v5
	s_and_b64 vcc, s[28:29], vcc
	v_mfma_f32_32x32x16_bf16 v[16:31], v[10:13], v[232:235], v[16:31]
	v_cndmask_b32_e32 v10, v2, v210, vcc
	ds_read_b128 v[2:5], v226 offset:160
	v_fmamk_f32 v11, v84, 0x3e0293ee, v151
	v_cmp_lt_i32_e32 vcc, -8, v6
	s_and_b64 vcc, s[28:29], vcc
	v_fmamk_f32 v83, v92, 0x3e0293ee, v151
	s_waitcnt lgkmcnt(0)
	v_add_f32_e32 v2, v11, v2
	v_cndmask_b32_e32 v11, v2, v210, vcc
	v_fmamk_f32 v2, v85, 0x3e0293ee, v151
	v_cmp_lt_i32_e32 vcc, -9, v6
	v_add_f32_e32 v2, v2, v3
	s_and_b64 vcc, s[28:29], vcc
	v_cndmask_b32_e32 v12, v2, v210, vcc
	v_fmamk_f32 v2, v86, 0x3e0293ee, v151
	v_cmp_lt_i32_e32 vcc, -10, v6
	v_add_f32_e32 v2, v2, v4
	s_and_b64 vcc, s[28:29], vcc
	v_cndmask_b32_e32 v13, v2, v210, vcc
	v_fmamk_f32 v2, v87, 0x3e0293ee, v151
	v_cmp_lt_i32_e32 vcc, -11, v6
	v_add_f32_e32 v2, v2, v5
	s_and_b64 vcc, s[28:29], vcc
	v_cndmask_b32_e32 v14, v2, v210, vcc
	ds_read_b128 v[2:5], v226 offset:192
	v_cmp_lt_i32_e32 vcc, -16, v6
	s_and_b64 vcc, s[28:29], vcc
	v_exp_f32_e32 v101, v7
	v_exp_f32_e32 v105, v8
	s_waitcnt lgkmcnt(0)
; #define LAS __attribute__((address_space(3)))
; #define MFMA32(a, b, c) __builtin_amdgcn_mfma_f32_32x32x16_bf16((a), (b), (c), 0, 0, 0)
; __device__ __forceinline__ float fast_exp2(float x) { return __builtin_amdgcn_exp2f(x); }
; template <int MODE>
; __device__ __forceinline__ void attn_item(LAS unsigned char* lds, const AttnArgs& a, const int tid) {
;     ...
;             for (int kt = 0; kt < 2; ++kt) {
;                 if (MODE == 1) {
;                     const LAS float* csb = (const LAS float*)(lds + A_CS) + t * 64 + 32 * kt + 4 * h;
;                     const int mb = t * 64 + 32 * kt + 4 * h - (qw0 + r);
; #pragma unroll
;                     for (int g = 0; g < 4; ++g) { const f32x4 cv = *(const LAS f32x4*)(csb + 8 * g);
; #pragma unroll
;                         for (int e = 0; e < 4; ++e) { float x = fmaf(s[kt][4 * g + e], sc, addc) + cv[e]; if (diag && (mb + 8 * g + e > 0)) x = -1e30f; s[kt][4 * g + e] = x; } }
;                 } else if (MODE == 2) {
;                     if (near) {
;                         const LAS float* lut = (const LAS float*)(lds + A_LUT) + (t * 64 + 32 * kt + 4 * h - (qw0 + r) + 191);
; #pragma unroll
;                         for (int i = 0; i < 16; ++i) s[kt][i] = fmaf(s[kt][i], sc, lut[8 * (i >> 2) + (i & 3)]);
;                     } else {
; #pragma unroll
;                         for (int i = 0; i < 16; ++i) s[kt][i] = fmaf(s[kt][i], sc, addc);
;                     }
;                 } else {
; #pragma unroll
;                     for (int i = 0; i < 16; ++i) s[kt][i] = fmaf(s[kt][i], sc, addc);
;                 }
;                 float ls = 0.f;
; #pragma unroll
;                 for (int i = 0; i < 16; ++i) { const float pv = fast_exp2(s[kt][i]); s[kt][i] = pv; ls += pv; }
;                 l += ls;
; #pragma unroll
;                 for (int ss = 0; ss < 2; ++ss) { u32x4 w;
;                     w.x = pk2(s[kt][8 * ss + 0], s[kt][8 * ss + 1]); w.y = pk2(s[kt][8 * ss + 2], s[kt][8 * ss + 3]);
;                     w.z = pk2(s[kt][8 * ss + 4], s[kt][8 * ss + 5]); w.w = pk2(s[kt][8 * ss + 6], s[kt][8 * ss + 7]);
;                     pf[ss] = __builtin_bit_cast(bf16x8, w); }
; #pragma unroll
;                 for (int jj = 0; jj < 8; ++jj) { const int j = 8 * kt + jj;
;                     o[jj & 3] = MFMA32(vf[j % VD], pf[jj >> 2], o[jj & 3]);
;                     if (j + VD < 16) AT_VLD(j + VD); }
	v_add_f32_e32 v2, v15, v2
	v_cndmask_b32_e32 v15, v2, v210, vcc
	v_fmamk_f32 v2, v89, 0x3e0293ee, v151
	v_cmp_lt_i32_e32 vcc, s35, v6
	v_add_f32_e32 v2, v2, v3
	s_and_b64 vcc, s[28:29], vcc
	v_cndmask_b32_e32 v80, v2, v210, vcc
	v_fmamk_f32 v2, v90, 0x3e0293ee, v151
	v_cmp_lt_i32_e32 vcc, s61, v6
	v_add_f32_e32 v2, v2, v4
	s_and_b64 vcc, s[28:29], vcc
	v_cndmask_b32_e32 v81, v2, v210, vcc
	v_fmamk_f32 v2, v91, 0x3e0293ee, v151
	v_cmp_lt_i32_e32 vcc, s62, v6
	v_add_f32_e32 v2, v2, v5
	s_and_b64 vcc, s[28:29], vcc
	v_cndmask_b32_e32 v82, v2, v210, vcc
	ds_read_b128 v[2:5], v226 offset:224
	v_cmp_lt_i32_e32 vcc, s63, v6
	s_and_b64 vcc, s[28:29], vcc
	v_exp_f32_e32 v103, v9
	v_exp_f32_e32 v107, v10
	s_waitcnt lgkmcnt(0)
	v_add_f32_e32 v2, v83, v2
	v_cndmask_b32_e32 v83, v2, v210, vcc
	v_fmamk_f32 v2, v93, 0x3e0293ee, v151
	v_cmp_lt_i32_e32 vcc, s40, v6
	v_add_f32_e32 v2, v2, v3
	s_and_b64 vcc, s[28:29], vcc
	v_cndmask_b32_e32 v84, v2, v210, vcc
	v_fmamk_f32 v2, v94, 0x3e0293ee, v151
	v_cmp_lt_i32_e32 vcc, s81, v6
	v_add_f32_e32 v2, v2, v4
	s_and_b64 vcc, s[28:29], vcc
	v_cndmask_b32_e32 v4, v2, v210, vcc
	v_fmamk_f32 v2, v95, 0x3e0293ee, v151
	v_cmp_lt_i32_e32 vcc, s23, v6
	v_add_f32_e32 v2, v2, v5
	s_and_b64 vcc, s[28:29], vcc
	v_cndmask_b32_e32 v5, v2, v210, vcc
	v_add_f32_e32 v2, v100, v0
	v_add_f32_e32 v3, v101, v1
	v_exp_f32_e32 v109, v11
	v_add_f32_e32 v2, v104, v2
	v_add_f32_e32 v3, v105, v3
	v_exp_f32_e32 v157, v12
	v_add_f32_e32 v2, v102, v2
	v_add_f32_e32 v3, v103, v3
	v_exp_f32_e32 v111, v13
	v_add_f32_e32 v2, v106, v2
	v_add_f32_e32 v3, v107, v3
	v_exp_f32_e32 v161, v14
	ds_read_b64_tr_b16 v[10:11], v223 offset:24576
	ds_read_b64_tr_b16 v[12:13], v224 offset:24576
	v_exp_f32_e32 v159, v15
	v_add_f32_e32 v2, v108, v2
	v_add_f32_e32 v3, v109, v3
	v_exp_f32_e32 v165, v80
	v_add_f32_e32 v2, v156, v2
	v_add_f32_e32 v3, v157, v3
	v_exp_f32_e32 v163, v81
	v_add_f32_e32 v2, v110, v2
	v_add_f32_e32 v3, v111, v3
	v_exp_f32_e32 v169, v82
	v_add_f32_e32 v2, v160, v2
	v_add_f32_e32 v3, v161, v3
	v_cvt_pk_bf16_f32 v6, v101, v105
	v_cvt_pk_bf16_f32 v7, v103, v107
	v_cvt_pk_bf16_f32 v8, v109, v157
	v_cvt_pk_bf16_f32 v9, v111, v161
	v_exp_f32_e32 v167, v83
	v_add_f32_e32 v2, v158, v2
	v_add_f32_e32 v3, v159, v3
	v_mfma_f32_32x32x16_bf16 v[64:79], v[236:239], v[6:9], v[64:79]
	v_exp_f32_e32 v173, v84
	v_add_f32_e32 v2, v164, v2
	v_add_f32_e32 v3, v165, v3
	v_exp_f32_e32 v171, v4
	v_add_f32_e32 v2, v162, v2
	v_add_f32_e32 v3, v163, v3
	v_exp_f32_e32 v155, v5
	v_add_f32_e32 v2, v168, v2
	v_add_f32_e32 v3, v169, v3
	ds_read_b64_tr_b16 v[84:85], v217 offset:28672
	ds_read_b64_tr_b16 v[86:87], v218 offset:28672
	v_mfma_f32_32x32x16_bf16 v[48:63], v[240:243], v[6:9], v[48:63]
	ds_read_b64_tr_b16 v[80:81], v219 offset:28672
	ds_read_b64_tr_b16 v[82:83], v220 offset:28672
	v_add_f32_e64 v2, v166, v2
	v_add_f32_e64 v3, v167, v3
	v_cvt_pk_bf16_f32 v4, v167, v173
	v_add_f32_e32 v2, v172, v2
	v_add_f32_e32 v3, v173, v3
	v_cvt_pk_bf16_f32 v5, v171, v155
	v_add_f32_e32 v2, v170, v2
	v_add_f32_e32 v3, v171, v3
	v_mfma_f32_32x32x16_bf16 v[32:47], v[96:99], v[6:9], v[32:47]
	v_add_f32_e64 v14, v154, v2
	v_add_f32_e64 v15, v155, v3
	v_cvt_pk_bf16_f32 v2, v159, v165
	v_cvt_pk_bf16_f32 v3, v163, v169
	v_add_f32_e32 v154, v14, v15
	s_waitcnt lgkmcnt(4)
	v_mfma_f32_32x32x16_bf16 v[16:31], v[10:13], v[6:9], v[16:31]
	ds_read_b64_tr_b16 v[6:7], v221 offset:28672
	ds_read_b64_tr_b16 v[8:9], v222 offset:28672
	ds_read_b64_tr_b16 v[10:11], v223 offset:28672
	ds_read_b64_tr_b16 v[12:13], v224 offset:28672
	s_waitcnt lgkmcnt(6)
	v_mfma_f32_32x32x16_bf16 v[64:79], v[84:87], v[2:5], v[64:79]
	s_waitcnt lgkmcnt(4)
	v_mfma_f32_32x32x16_bf16 v[48:63], v[80:83], v[2:5], v[48:63]
	s_waitcnt lgkmcnt(2)
	v_mfma_f32_32x32x16_bf16 v[32:47], v[6:9], v[2:5], v[32:47]
	s_waitcnt lgkmcnt(0)
	v_mfma_f32_32x32x16_bf16 v[16:31], v[10:13], v[2:5], v[16:31]

; template <int MODE>
; __device__ __forceinline__ void attn_item(LAS unsigned char* lds, const AttnArgs& a, const int tid) {
;     ...
;         if (t <= tw) {
;             LAS unsigned char* kb = lds + b * 32768;
;             f32x16 s[2];
; #pragma unroll
;             for (int i = 0; i < 16; ++i) { s[0][i] = 0.f; s[1][i] = 0.f; }
;             constexpr int KD = AT_KD, VD = AT_VD;
;             bf16x8 kf[KD];
;     ...
; #pragma unroll
;             for (int i = 0; i < KD; ++i) kf[i] = AT_KLD(i);
; #pragma unroll
;             for (int i = 0; i < 2 * NKS; ++i) { s[i & 1] = MFMA32(kf[i % KD], qf[i >> 1], s[i & 1]); if (i + KD < 2 * NKS) kf[i % KD] = AT_KLD(i + KD); }
;     ...
;             bf16x8 vf[VD];
;     ...
; #pragma unroll
;             for (int j = 0; j < VD; ++j) AT_VLD(j);
;             const float sc = a.sc;
;             const bool diag = (MODE == 1) && (t * 64 + 63 > qw0);
;             const bool near = (MODE == 2) && (t >= tw - 2);
;             bf16x8 pf[2];
; #pragma unroll
;             for (int kt = 0; kt < 2; ++kt) {
;                 if (MODE == 1) {
;                     const LAS float* csb = (const LAS float*)(lds + A_CS) + t * 64 + 32 * kt + 4 * h;
;                     const int mb = t * 64 + 32 * kt + 4 * h - (qw0 + r);
; #pragma unroll
;                     for (int g = 0; g < 4; ++g) { const f32x4 cv = *(const LAS f32x4*)(csb + 8 * g);
; #pragma unroll
;                         for (int e = 0; e < 4; ++e) { float x = fmaf(s[kt][4 * g + e], sc, addc) + cv[e]; if (diag && (mb + 8 * g + e > 0)) x = -1e30f; s[kt][4 * g + e] = x; } }
;                 } else if (MODE == 2) {
;                     if (near) {
;                         const LAS float* lut = (const LAS float*)(lds + A_LUT) + (t * 64 + 32 * kt + 4 * h - (qw0 + r) + 191);
; #pragma unroll
;                         for (int i = 0; i < 16; ++i) s[kt][i] = fmaf(s[kt][i], sc, lut[8 * (i >> 2) + (i & 3)]);
;                     } else {
; #pragma unroll
;                         for (int i = 0; i < 16; ++i) s[kt][i] = fmaf(s[kt][i], sc, addc);
;                     }
;                 } else {
; #pragma unroll
;                     for (int i = 0; i < 16; ++i) s[kt][i] = fmaf(s[kt][i], sc, addc);
;                 }
;                 float ls = 0.f;
; #pragma unroll
;                 for (int i = 0; i < 16; ++i) { const float pv = fast_exp2(s[kt][i]); s[kt][i] = pv; ls += pv; }
;                 l += ls;
.LBB0_65:
	s_cmp_ge_i32 s34, s55
	s_cbranch_scc1 .LBB0_67
	s_cmp_gt_i32 s60, s51
	s_cbranch_scc1 .Lmy_fox_diag2
	ds_read_b128 v[2:5], v198 offset:32768
	ds_read_b128 v[6:9], v198 offset:40960
	ds_read_b128 v[10:13], v199 offset:32768
	ds_read_b128 v[156:159], v199 offset:40960
	s_cmp_gt_i32 s60, s51
	s_waitcnt lgkmcnt(3)
	v_mfma_f32_32x32x16_bf16 v[96:111], v[2:5], v[116:119], 0
	ds_read_b128 v[2:5], v200 offset:32768
	v_subrev_u32_e32 v0, 63, v227
	s_cselect_b64 s[34:35], -1, 0
	s_movk_i32 s62, 0xffef
	s_movk_i32 s63, 0xffee
	s_waitcnt lgkmcnt(3)
	v_mfma_f32_32x32x16_bf16 v[80:95], v[6:9], v[116:119], 0
	ds_read_b128 v[6:9], v200 offset:40960
	s_movk_i32 s97, 0xffed
	s_movk_i32 s40, 0xffe8
	s_movk_i32 s81, 0xffe7
	s_movk_i32 s23, 0xffe6
	s_movk_i32 s0, 0xffe5
	s_waitcnt lgkmcnt(3)
	v_mfma_f32_32x32x16_bf16 v[96:111], v[10:13], v[120:123], v[96:111]
	ds_read_b128 v[10:13], v201 offset:32768
	s_waitcnt lgkmcnt(3)
	v_mfma_f32_32x32x16_bf16 v[80:95], v[156:159], v[120:123], v[80:95]
	ds_read_b128 v[156:159], v201 offset:40960
	s_waitcnt lgkmcnt(3)
	v_mfma_f32_32x32x16_bf16 v[96:111], v[2:5], v[124:127], v[96:111]
	ds_read_b128 v[2:5], v213 offset:32768
	s_waitcnt lgkmcnt(3)
	v_mfma_f32_32x32x16_bf16 v[80:95], v[6:9], v[124:127], v[80:95]
	ds_read_b128 v[6:9], v213 offset:40960
	s_waitcnt lgkmcnt(3)
	v_mfma_f32_32x32x16_bf16 v[96:111], v[10:13], v[128:131], v[96:111]
	ds_read_b128 v[10:13], v214 offset:32768
	s_waitcnt lgkmcnt(3)
	v_mfma_f32_32x32x16_bf16 v[80:95], v[156:159], v[128:131], v[80:95]
	ds_read_b128 v[156:159], v214 offset:40960
	s_waitcnt lgkmcnt(3)
	v_mfma_f32_32x32x16_bf16 v[96:111], v[2:5], v[132:135], v[96:111]
	ds_read_b128 v[2:5], v215 offset:32768
	s_waitcnt lgkmcnt(3)
	v_mfma_f32_32x32x16_bf16 v[80:95], v[6:9], v[132:135], v[80:95]
	ds_read_b128 v[6:9], v215 offset:40960
	s_waitcnt lgkmcnt(3)
	v_mfma_f32_32x32x16_bf16 v[96:111], v[10:13], v[136:139], v[96:111]
	ds_read_b128 v[10:13], v216 offset:32768
	s_waitcnt lgkmcnt(3)
	v_mfma_f32_32x32x16_bf16 v[80:95], v[156:159], v[136:139], v[80:95]
	ds_read_b128 v[156:159], v216 offset:40960
	s_waitcnt lgkmcnt(3)
	v_mfma_f32_32x32x16_bf16 v[96:111], v[2:5], v[140:143], v[96:111]
	s_waitcnt lgkmcnt(2)
	v_mfma_f32_32x32x16_bf16 v[80:95], v[6:9], v[140:143], v[80:95]
	s_waitcnt lgkmcnt(1)
	v_mfma_f32_32x32x16_bf16 v[96:111], v[10:13], v[144:147], v[96:111]
	ds_read_b64_tr_b16 v[6:7], v217 offset:49152
	ds_read_b64_tr_b16 v[8:9], v218 offset:49152
	ds_read_b64_tr_b16 v[10:11], v219 offset:49152
	ds_read_b64_tr_b16 v[12:13], v220 offset:49152
	ds_read_b64_tr_b16 v[2:3], v221 offset:49152
	ds_read_b64_tr_b16 v[4:5], v222 offset:49152
	s_nop 5
	v_fmamk_f32 v14, v96, 0x3e0293ee, v151
	s_waitcnt lgkmcnt(6)
	v_mfma_f32_32x32x16_bf16 v[80:95], v[156:159], v[144:147], v[80:95]
	ds_read_b128 v[156:159], v226 offset:256
	ds_read_b128 v[160:163], v226 offset:288
	v_fmamk_f32 v15, v97, 0x3e0293ee, v151
	v_fmamk_f32 v96, v98, 0x3e0293ee, v151
	s_waitcnt lgkmcnt(1)
	v_add_f32_e32 v14, v14, v156
	v_add_f32_e32 v15, v15, v157
	v_add_f32_e32 v96, v96, v158
	v_mov_b32_e32 v155, v96
	v_fmamk_f32 v96, v99, 0x3e0293ee, v151
	v_add_f32_e32 v96, v96, v159
	v_mov_b32_e32 v156, v96
	v_fmamk_f32 v96, v100, 0x3e0293ee, v151
	s_waitcnt lgkmcnt(0)
	v_add_f32_e32 v96, v96, v160
	v_mov_b32_e32 v157, v96
	v_fmamk_f32 v96, v101, 0x3e0293ee, v151
	v_add_f32_e32 v96, v96, v161
	v_mov_b32_e32 v101, v96
	v_fmamk_f32 v96, v102, 0x3e0293ee, v151
	v_add_f32_e32 v96, v96, v162
	v_mov_b32_e32 v158, v96
	v_fmamk_f32 v96, v103, 0x3e0293ee, v151
	v_add_f32_e32 v96, v96, v163
	v_mov_b32_e32 v103, v96
	ds_read_b128 v[96:99], v226 offset:320
	v_fmamk_f32 v100, v104, 0x3e0293ee, v151
	v_exp_f32_e32 v14, v14
	s_waitcnt lgkmcnt(0)
	v_add_f32_e32 v96, v100, v96
	v_mov_b32_e32 v159, v96
	v_fmamk_f32 v96, v105, 0x3e0293ee, v151
	v_add_f32_e32 v96, v96, v97
	v_mov_b32_e32 v105, v96
	v_fmamk_f32 v96, v106, 0x3e0293ee, v151
	v_add_f32_e32 v96, v96, v98
	v_mov_b32_e32 v161, v96
	v_fmamk_f32 v96, v107, 0x3e0293ee, v151
	v_add_f32_e32 v96, v96, v99
	v_mov_b32_e32 v107, v96
	ds_read_b128 v[96:99], v226 offset:352
	v_fmamk_f32 v100, v108, 0x3e0293ee, v151
	v_exp_f32_e32 v104, v155
	s_waitcnt lgkmcnt(0)
	v_add_f32_e32 v96, v100, v96
	v_fmamk_f32 v100, v109, 0x3e0293ee, v151
	v_add_f32_e32 v97, v100, v97
	v_fmamk_f32 v100, v110, 0x3e0293ee, v151
	v_add_f32_e32 v98, v100, v98
	v_fmamk_f32 v100, v111, 0x3e0293ee, v151
	v_add_f32_e32 v99, v100, v99
	v_exp_f32_e32 v100, v15
	v_exp_f32_e32 v102, v156
	v_exp_f32_e32 v106, v157
	v_exp_f32_e32 v108, v101
	v_exp_f32_e32 v156, v158
	v_exp_f32_e32 v110, v103
	v_exp_f32_e32 v168, v96
	v_exp_f32_e32 v166, v97
	v_exp_f32_e32 v172, v98
	v_exp_f32_e32 v170, v99
	v_cvt_pk_bf16_f32 v96, v14, v100
	v_cvt_pk_bf16_f32 v97, v104, v102
	v_cvt_pk_bf16_f32 v98, v106, v108
	v_cvt_pk_bf16_f32 v99, v156, v110
	v_exp_f32_e32 v160, v159
	v_exp_f32_e32 v158, v105
	v_mfma_f32_32x32x16_bf16 v[64:79], v[6:9], v[96:99], v[64:79]
	ds_read_b64_tr_b16 v[6:7], v223 offset:49152
	ds_read_b64_tr_b16 v[8:9], v224 offset:49152
	v_exp_f32_e32 v164, v161
	v_exp_f32_e32 v162, v107
	v_cvt_pk_bf16_f32 v232, v160, v158
	v_cvt_pk_bf16_f32 v234, v168, v166
	v_cvt_pk_bf16_f32 v235, v172, v170
	v_cvt_pk_bf16_f32 v233, v164, v162
	v_mfma_f32_32x32x16_bf16 v[48:63], v[10:13], v[96:99], v[48:63]
	ds_read_b64_tr_b16 v[10:11], v217 offset:53248
	ds_read_b64_tr_b16 v[12:13], v218 offset:53248
	v_add_f32_e32 v0, 0, v14
	v_fmamk_f32 v15, v88, 0x3e0293ee, v151
	v_mfma_f32_32x32x16_bf16 v[32:47], v[2:5], v[96:99], v[32:47]
	ds_read_b64_tr_b16 v[2:3], v219 offset:53248
	ds_read_b64_tr_b16 v[4:5], v220 offset:53248
	s_waitcnt lgkmcnt(4)
; #define MFMA32(a, b, c) __builtin_amdgcn_mfma_f32_32x32x16_bf16((a), (b), (c), 0, 0, 0)
; __device__ __forceinline__ unsigned pk2(float lo, float hi) { const f32x2v v = {lo, hi}; return __builtin_bit_cast(unsigned, __builtin_convertvector(v, bf16x2v)); }
; __device__ __forceinline__ float fast_exp2(float x) { return __builtin_amdgcn_exp2f(x); }
; template <int MODE>
; __device__ __forceinline__ void attn_item(LAS unsigned char* lds, const AttnArgs& a, const int tid) {
;     ...
;                 float ls = 0.f;
; #pragma unroll
;                 for (int i = 0; i < 16; ++i) { const float pv = fast_exp2(s[kt][i]); s[kt][i] = pv; ls += pv; }
;                 l += ls;
; #pragma unroll
;                 for (int ss = 0; ss < 2; ++ss) { u32x4 w;
;                     w.x = pk2(s[kt][8 * ss + 0], s[kt][8 * ss + 1]); w.y = pk2(s[kt][8 * ss + 2], s[kt][8 * ss + 3]);
;                     w.z = pk2(s[kt][8 * ss + 4], s[kt][8 * ss + 5]); w.w = pk2(s[kt][8 * ss + 6], s[kt][8 * ss + 7]);
;                     pf[ss] = __builtin_bit_cast(bf16x8, w); }
; #pragma unroll
;                 for (int jj = 0; jj < 8; ++jj) { const int j = 8 * kt + jj;
;                     o[jj & 3] = MFMA32(vf[j % VD], pf[jj >> 2], o[jj & 3]);
;                     if (j + VD < 16) AT_VLD(j + VD); }
;             }
	v_mfma_f32_32x32x16_bf16 v[16:31], v[6:9], v[96:99], v[16:31]
	ds_read_b64_tr_b16 v[6:7], v221 offset:53248
	ds_read_b64_tr_b16 v[8:9], v222 offset:53248
	s_waitcnt lgkmcnt(4)
	v_mfma_f32_32x32x16_bf16 v[64:79], v[10:13], v[232:235], v[64:79]
	ds_read_b64_tr_b16 v[10:11], v223 offset:53248
	ds_read_b64_tr_b16 v[12:13], v224 offset:53248
	ds_read_b64_tr_b16 v[236:237], v217 offset:57344
	ds_read_b64_tr_b16 v[238:239], v218 offset:57344
	ds_read_b64_tr_b16 v[240:241], v219 offset:57344
	ds_read_b64_tr_b16 v[242:243], v220 offset:57344
	ds_read_b64_tr_b16 v[96:97], v221 offset:57344
	ds_read_b64_tr_b16 v[98:99], v222 offset:57344
	s_waitcnt lgkmcnt(10)
	v_mfma_f32_32x32x16_bf16 v[48:63], v[2:5], v[232:235], v[48:63]
	ds_read_b128 v[2:5], v226 offset:384
	s_waitcnt lgkmcnt(9)
	v_mfma_f32_32x32x16_bf16 v[32:47], v[6:9], v[232:235], v[32:47]
	v_subrev_u32_e32 v6, 31, v227
	v_fmamk_f32 v7, v80, 0x3e0293ee, v151
	s_waitcnt lgkmcnt(0)
	v_add_f32_e32 v2, v7, v2
	v_mov_b32_e32 v7, v2
	v_fmamk_f32 v2, v81, 0x3e0293ee, v151
	v_add_f32_e32 v2, v2, v3
	v_mov_b32_e32 v8, v2
	v_fmamk_f32 v2, v82, 0x3e0293ee, v151
	v_add_f32_e32 v2, v2, v4
	v_mov_b32_e32 v9, v2
	v_fmamk_f32 v2, v83, 0x3e0293ee, v151
	v_add_f32_e32 v2, v2, v5
	v_mfma_f32_32x32x16_bf16 v[16:31], v[10:13], v[232:235], v[16:31]
	v_mov_b32_e32 v10, v2
	ds_read_b128 v[2:5], v226 offset:416
	v_fmamk_f32 v11, v84, 0x3e0293ee, v151
	v_fmamk_f32 v83, v92, 0x3e0293ee, v151
	s_waitcnt lgkmcnt(0)
	v_add_f32_e32 v2, v11, v2
	v_mov_b32_e32 v11, v2
	v_fmamk_f32 v2, v85, 0x3e0293ee, v151
	v_add_f32_e32 v2, v2, v3
	v_mov_b32_e32 v12, v2
	v_fmamk_f32 v2, v86, 0x3e0293ee, v151
	v_add_f32_e32 v2, v2, v4
	v_mov_b32_e32 v13, v2
	v_fmamk_f32 v2, v87, 0x3e0293ee, v151
	v_add_f32_e32 v2, v2, v5
	v_mov_b32_e32 v14, v2
	ds_read_b128 v[2:5], v226 offset:448
	v_exp_f32_e32 v101, v7
	v_exp_f32_e32 v105, v8
	s_waitcnt lgkmcnt(0)
	v_add_f32_e32 v2, v15, v2
	v_mov_b32_e32 v15, v2
	v_fmamk_f32 v2, v89, 0x3e0293ee, v151
	v_add_f32_e32 v2, v2, v3
	v_mov_b32_e32 v80, v2
	v_fmamk_f32 v2, v90, 0x3e0293ee, v151
	v_add_f32_e32 v2, v2, v4
	v_mov_b32_e32 v81, v2
	v_fmamk_f32 v2, v91, 0x3e0293ee, v151
	v_add_f32_e32 v2, v2, v5
	v_mov_b32_e32 v82, v2
	ds_read_b128 v[2:5], v226 offset:480
	v_exp_f32_e32 v103, v9
	v_exp_f32_e32 v107, v10
	s_waitcnt lgkmcnt(0)
	v_add_f32_e32 v2, v83, v2
	v_mov_b32_e32 v83, v2
	v_fmamk_f32 v2, v93, 0x3e0293ee, v151
	v_add_f32_e32 v2, v2, v3
	v_mov_b32_e32 v84, v2
	v_fmamk_f32 v2, v94, 0x3e0293ee, v151
	v_add_f32_e32 v2, v2, v4
	v_mov_b32_e32 v4, v2
	v_fmamk_f32 v2, v95, 0x3e0293ee, v151
	v_add_f32_e32 v2, v2, v5
	v_mov_b32_e32 v5, v2
	v_add_f32_e32 v2, v100, v0
	v_add_f32_e32 v3, v101, v1
	v_exp_f32_e32 v109, v11
	v_add_f32_e32 v2, v104, v2
	v_add_f32_e32 v3, v105, v3
	v_exp_f32_e32 v157, v12
	v_add_f32_e32 v2, v102, v2
	v_add_f32_e32 v3, v103, v3
	v_exp_f32_e32 v111, v13
	v_add_f32_e32 v2, v106, v2
	v_add_f32_e32 v3, v107, v3
	v_exp_f32_e32 v161, v14
	ds_read_b64_tr_b16 v[10:11], v223 offset:57344
	ds_read_b64_tr_b16 v[12:13], v224 offset:57344
	v_exp_f32_e32 v159, v15
	v_add_f32_e32 v2, v108, v2
	v_add_f32_e32 v3, v109, v3
	v_exp_f32_e32 v165, v80
	v_add_f32_e32 v2, v156, v2
	v_add_f32_e32 v3, v157, v3
	v_exp_f32_e32 v163, v81
	v_add_f32_e32 v2, v110, v2
	v_add_f32_e32 v3, v111, v3
	v_exp_f32_e32 v169, v82
	v_add_f32_e32 v2, v160, v2
	v_add_f32_e32 v3, v161, v3
	v_cvt_pk_bf16_f32 v6, v101, v105
	v_cvt_pk_bf16_f32 v7, v103, v107
	v_cvt_pk_bf16_f32 v8, v109, v157
	v_cvt_pk_bf16_f32 v9, v111, v161
	v_exp_f32_e32 v167, v83
	v_add_f32_e32 v2, v158, v2
	v_add_f32_e32 v3, v159, v3
	v_mfma_f32_32x32x16_bf16 v[64:79], v[236:239], v[6:9], v[64:79]
	v_exp_f32_e32 v173, v84
	v_add_f32_e32 v2, v164, v2
	v_add_f32_e32 v3, v165, v3
	v_exp_f32_e32 v171, v4
	v_add_f32_e32 v2, v162, v2
	v_add_f32_e32 v3, v163, v3
	v_exp_f32_e32 v155, v5
	v_add_f32_e32 v2, v168, v2
	v_add_f32_e32 v3, v169, v3
	ds_read_b64_tr_b16 v[84:85], v217 offset:61440
	ds_read_b64_tr_b16 v[86:87], v218 offset:61440
	v_mfma_f32_32x32x16_bf16 v[48:63], v[240:243], v[6:9], v[48:63]
	ds_read_b64_tr_b16 v[80:81], v219 offset:61440
	ds_read_b64_tr_b16 v[82:83], v220 offset:61440
	v_add_f32_e64 v2, v166, v2
	v_add_f32_e64 v3, v167, v3
	v_cvt_pk_bf16_f32 v4, v167, v173
	v_add_f32_e32 v2, v172, v2
	v_add_f32_e32 v3, v173, v3
	v_cvt_pk_bf16_f32 v5, v171, v155
	v_add_f32_e32 v2, v170, v2
	v_add_f32_e32 v3, v171, v3
	v_mfma_f32_32x32x16_bf16 v[32:47], v[96:99], v[6:9], v[32:47]
	v_add_f32_e64 v14, v154, v2
	v_add_f32_e64 v15, v155, v3
	v_cvt_pk_bf16_f32 v2, v159, v165
	v_cvt_pk_bf16_f32 v3, v163, v169
	v_add_f32_e32 v154, v14, v15
	s_waitcnt lgkmcnt(4)
	v_mfma_f32_32x32x16_bf16 v[16:31], v[10:13], v[6:9], v[16:31]
	ds_read_b64_tr_b16 v[6:7], v221 offset:61440
	ds_read_b64_tr_b16 v[8:9], v222 offset:61440
	ds_read_b64_tr_b16 v[10:11], v223 offset:61440
	ds_read_b64_tr_b16 v[12:13], v224 offset:61440
	s_waitcnt lgkmcnt(6)
	v_mfma_f32_32x32x16_bf16 v[64:79], v[84:87], v[2:5], v[64:79]
	s_waitcnt lgkmcnt(4)
	v_mfma_f32_32x32x16_bf16 v[48:63], v[80:83], v[2:5], v[48:63]
	s_waitcnt lgkmcnt(2)
	v_mfma_f32_32x32x16_bf16 v[32:47], v[6:9], v[2:5], v[32:47]
	s_waitcnt lgkmcnt(0)
	v_mfma_f32_32x32x16_bf16 v[16:31], v[10:13], v[2:5], v[16:31]
	s_branch .LBB0_67
; #define LAS __attribute__((address_space(3)))
; template <int MODE>
; __device__ __forceinline__ void attn_item(LAS unsigned char* lds, const AttnArgs& a, const int tid) {
;     ...
;             const bool diag = (MODE == 1) && (t * 64 + 63 > qw0);
;             const bool near = (MODE == 2) && (t >= tw - 2);
;             bf16x8 pf[2];
; #pragma unroll
;             for (int kt = 0; kt < 2; ++kt) {
;                 if (MODE == 1) {
;                     const LAS float* csb = (const LAS float*)(lds + A_CS) + t * 64 + 32 * kt + 4 * h;
;                     const int mb = t * 64 + 32 * kt + 4 * h - (qw0 + r);
; #pragma unroll
;                     for (int g = 0; g < 4; ++g) { const f32x4 cv = *(const LAS f32x4*)(csb + 8 * g);
; #pragma unroll
;                         for (int e = 0; e < 4; ++e) { float x = fmaf(s[kt][4 * g + e], sc, addc) + cv[e]; if (diag && (mb + 8 * g + e > 0)) x = -1e30f; s[kt][4 * g + e] = x; } }
.Lmy_fox_diag2:
	ds_read_b128 v[2:5], v198 offset:32768
	ds_read_b128 v[6:9], v198 offset:40960
	ds_read_b128 v[10:13], v199 offset:32768
	ds_read_b128 v[156:159], v199 offset:40960
	s_cmp_gt_i32 s60, s51
	s_waitcnt lgkmcnt(3)
	v_mfma_f32_32x32x16_bf16 v[96:111], v[2:5], v[116:119], 0
	ds_read_b128 v[2:5], v200 offset:32768
	v_subrev_u32_e32 v0, 63, v227
	s_cselect_b64 s[34:35], -1, 0
	v_cmp_lt_i32_e32 vcc, 0, v0
	s_and_b64 vcc, s[34:35], vcc
	s_movk_i32 s62, 0xffef
	s_movk_i32 s63, 0xffee
	s_waitcnt lgkmcnt(3)
	v_mfma_f32_32x32x16_bf16 v[80:95], v[6:9], v[116:119], 0
	ds_read_b128 v[6:9], v200 offset:40960
	s_movk_i32 s97, 0xffed
	s_movk_i32 s40, 0xffe8
	s_movk_i32 s81, 0xffe7
	s_movk_i32 s23, 0xffe6
	s_movk_i32 s0, 0xffe5
	s_waitcnt lgkmcnt(3)
	v_mfma_f32_32x32x16_bf16 v[96:111], v[10:13], v[120:123], v[96:111]
	ds_read_b128 v[10:13], v201 offset:32768
	s_waitcnt lgkmcnt(3)
	v_mfma_f32_32x32x16_bf16 v[80:95], v[156:159], v[120:123], v[80:95]
	ds_read_b128 v[156:159], v201 offset:40960
	s_waitcnt lgkmcnt(3)
	v_mfma_f32_32x32x16_bf16 v[96:111], v[2:5], v[124:127], v[96:111]
	ds_read_b128 v[2:5], v213 offset:32768
	s_waitcnt lgkmcnt(3)
	v_mfma_f32_32x32x16_bf16 v[80:95], v[6:9], v[124:127], v[80:95]
	ds_read_b128 v[6:9], v213 offset:40960
	s_waitcnt lgkmcnt(3)
	v_mfma_f32_32x32x16_bf16 v[96:111], v[10:13], v[128:131], v[96:111]
	ds_read_b128 v[10:13], v214 offset:32768
	s_waitcnt lgkmcnt(3)
	v_mfma_f32_32x32x16_bf16 v[80:95], v[156:159], v[128:131], v[80:95]
	ds_read_b128 v[156:159], v214 offset:40960
	s_waitcnt lgkmcnt(3)
	v_mfma_f32_32x32x16_bf16 v[96:111], v[2:5], v[132:135], v[96:111]
	ds_read_b128 v[2:5], v215 offset:32768
	s_waitcnt lgkmcnt(3)
	v_mfma_f32_32x32x16_bf16 v[80:95], v[6:9], v[132:135], v[80:95]
	ds_read_b128 v[6:9], v215 offset:40960
	s_waitcnt lgkmcnt(3)
	v_mfma_f32_32x32x16_bf16 v[96:111], v[10:13], v[136:139], v[96:111]
	ds_read_b128 v[10:13], v216 offset:32768
	s_waitcnt lgkmcnt(3)
	v_mfma_f32_32x32x16_bf16 v[80:95], v[156:159], v[136:139], v[80:95]
	ds_read_b128 v[156:159], v216 offset:40960
	s_waitcnt lgkmcnt(3)
	v_mfma_f32_32x32x16_bf16 v[96:111], v[2:5], v[140:143], v[96:111]
	s_waitcnt lgkmcnt(2)
	v_mfma_f32_32x32x16_bf16 v[80:95], v[6:9], v[140:143], v[80:95]
	s_waitcnt lgkmcnt(1)
	v_mfma_f32_32x32x16_bf16 v[96:111], v[10:13], v[144:147], v[96:111]
	ds_read_b64_tr_b16 v[6:7], v217 offset:49152
	ds_read_b64_tr_b16 v[8:9], v218 offset:49152
	ds_read_b64_tr_b16 v[10:11], v219 offset:49152
	ds_read_b64_tr_b16 v[12:13], v220 offset:49152
	ds_read_b64_tr_b16 v[2:3], v221 offset:49152
	ds_read_b64_tr_b16 v[4:5], v222 offset:49152
	s_nop 5
	v_fmamk_f32 v14, v96, 0x3e0293ee, v151
	s_waitcnt lgkmcnt(6)
	v_mfma_f32_32x32x16_bf16 v[80:95], v[156:159], v[144:147], v[80:95]
	ds_read_b128 v[156:159], v226 offset:256
	ds_read_b128 v[160:163], v226 offset:288
	v_fmamk_f32 v15, v97, 0x3e0293ee, v151
	v_fmamk_f32 v96, v98, 0x3e0293ee, v151
	s_waitcnt lgkmcnt(1)
	v_add_f32_e32 v14, v14, v156
	v_cndmask_b32_e32 v14, v14, v210, vcc
	v_cmp_lt_i32_e32 vcc, -1, v0
	v_add_f32_e32 v15, v15, v157
	s_and_b64 vcc, s[34:35], vcc
	v_cndmask_b32_e32 v15, v15, v210, vcc
	v_cmp_lt_i32_e32 vcc, -2, v0
	v_add_f32_e32 v96, v96, v158
	s_and_b64 vcc, s[34:35], vcc
	v_cndmask_b32_e32 v155, v96, v210, vcc
	v_fmamk_f32 v96, v99, 0x3e0293ee, v151
	v_cmp_lt_i32_e32 vcc, -3, v0
	v_add_f32_e32 v96, v96, v159
	s_and_b64 vcc, s[34:35], vcc
	v_cndmask_b32_e32 v156, v96, v210, vcc
	v_fmamk_f32 v96, v100, 0x3e0293ee, v151
	v_cmp_lt_i32_e32 vcc, -8, v0
	s_waitcnt lgkmcnt(0)
	v_add_f32_e32 v96, v96, v160
	s_and_b64 vcc, s[34:35], vcc
	v_cndmask_b32_e32 v157, v96, v210, vcc
	v_fmamk_f32 v96, v101, 0x3e0293ee, v151
	v_cmp_lt_i32_e32 vcc, -9, v0
	v_add_f32_e32 v96, v96, v161
	s_and_b64 vcc, s[34:35], vcc
	v_cndmask_b32_e32 v101, v96, v210, vcc
	v_fmamk_f32 v96, v102, 0x3e0293ee, v151
	v_cmp_lt_i32_e32 vcc, -10, v0
	v_add_f32_e32 v96, v96, v162
	s_and_b64 vcc, s[34:35], vcc
	v_cndmask_b32_e32 v158, v96, v210, vcc
	v_fmamk_f32 v96, v103, 0x3e0293ee, v151
	v_cmp_lt_i32_e32 vcc, -11, v0
	v_add_f32_e32 v96, v96, v163
	s_and_b64 vcc, s[34:35], vcc
	v_cndmask_b32_e32 v103, v96, v210, vcc
	ds_read_b128 v[96:99], v226 offset:320
	v_fmamk_f32 v100, v104, 0x3e0293ee, v151
	v_cmp_lt_i32_e32 vcc, -16, v0
	s_and_b64 vcc, s[34:35], vcc
	v_exp_f32_e32 v14, v14
	s_waitcnt lgkmcnt(0)
	v_add_f32_e32 v96, v100, v96
	v_cndmask_b32_e32 v159, v96, v210, vcc
	v_fmamk_f32 v96, v105, 0x3e0293ee, v151
	v_cmp_lt_i32_e32 vcc, s62, v0
	v_add_f32_e32 v96, v96, v97
	s_and_b64 vcc, s[34:35], vcc
	v_cndmask_b32_e32 v105, v96, v210, vcc
	v_fmamk_f32 v96, v106, 0x3e0293ee, v151
	v_cmp_lt_i32_e32 vcc, s63, v0
	v_add_f32_e32 v96, v96, v98
	s_and_b64 vcc, s[34:35], vcc
	v_cndmask_b32_e32 v161, v96, v210, vcc
	v_fmamk_f32 v96, v107, 0x3e0293ee, v151
	v_cmp_lt_i32_e32 vcc, s97, v0
	v_add_f32_e32 v96, v96, v99
	s_and_b64 vcc, s[34:35], vcc
	v_cndmask_b32_e32 v107, v96, v210, vcc
	ds_read_b128 v[96:99], v226 offset:352
	v_fmamk_f32 v100, v108, 0x3e0293ee, v151
	v_cmp_lt_i32_e32 vcc, s40, v0
	s_and_b64 vcc, s[34:35], vcc
	v_exp_f32_e32 v104, v155
	s_waitcnt lgkmcnt(0)
; #define LAS __attribute__((address_space(3)))
; template <int MODE>
; __device__ __forceinline__ void attn_item(LAS unsigned char* lds, const AttnArgs& a, const int tid) {
;     ...
;             const bool diag = (MODE == 1) && (t * 64 + 63 > qw0);
;             const bool near = (MODE == 2) && (t >= tw - 2);
;             bf16x8 pf[2];
; #pragma unroll
;             for (int kt = 0; kt < 2; ++kt) {
;                 if (MODE == 1) {
;                     const LAS float* csb = (const LAS float*)(lds + A_CS) + t * 64 + 32 * kt + 4 * h;
;                     const int mb = t * 64 + 32 * kt + 4 * h - (qw0 + r);
; #pragma unroll
;                     for (int g = 0; g < 4; ++g) { const f32x4 cv = *(const LAS f32x4*)(csb + 8 * g);
; #pragma unroll
;                         for (int e = 0; e < 4; ++e) { float x = fmaf(s[kt][4 * g + e], sc, addc) + cv[e]; if (diag && (mb + 8 * g + e > 0)) x = -1e30f; s[kt][4 * g + e] = x; } }
;                 } else if (MODE == 2) {
;                     if (near) {
;                         const LAS float* lut = (const LAS float*)(lds + A_LUT) + (t * 64 + 32 * kt + 4 * h - (qw0 + r) + 191);
; #pragma unroll
;                         for (int i = 0; i < 16; ++i) s[kt][i] = fmaf(s[kt][i], sc, lut[8 * (i >> 2) + (i & 3)]);
;                     } else {
; #pragma unroll
;                         for (int i = 0; i < 16; ++i) s[kt][i] = fmaf(s[kt][i], sc, addc);
;                     }
;                 } else {
; #pragma unroll
;                     for (int i = 0; i < 16; ++i) s[kt][i] = fmaf(s[kt][i], sc, addc);
;                 }
;                 float ls = 0.f;
; #pragma unroll
;                 for (int i = 0; i < 16; ++i) { const float pv = fast_exp2(s[kt][i]); s[kt][i] = pv; ls += pv; }
;                 l += ls;
; #pragma unroll
;                 for (int ss = 0; ss < 2; ++ss) { u32x4 w;
;                     w.x = pk2(s[kt][8 * ss + 0], s[kt][8 * ss + 1]); w.y = pk2(s[kt][8 * ss + 2], s[kt][8 * ss + 3]);
;                     w.z = pk2(s[kt][8 * ss + 4], s[kt][8 * ss + 5]); w.w = pk2(s[kt][8 * ss + 6], s[kt][8 * ss + 7]);
;                     pf[ss] = __builtin_bit_cast(bf16x8, w); }
; #pragma unroll
;                 for (int jj = 0; jj < 8; ++jj) { const int j = 8 * kt + jj;
;                     o[jj & 3] = MFMA32(vf[j % VD], pf[jj >> 2], o[jj & 3]);
;                     if (j + VD < 16) AT_VLD(j + VD); }
;             }
	v_add_f32_e32 v96, v100, v96
	v_cndmask_b32_e32 v96, v96, v210, vcc
	v_fmamk_f32 v100, v109, 0x3e0293ee, v151
	v_cmp_lt_i32_e32 vcc, s81, v0
	v_add_f32_e32 v97, v100, v97
	s_and_b64 vcc, s[34:35], vcc
	v_fmamk_f32 v100, v110, 0x3e0293ee, v151
	v_cndmask_b32_e32 v97, v97, v210, vcc
	v_add_f32_e32 v98, v100, v98
	v_cmp_lt_i32_e32 vcc, s23, v0
	v_fmamk_f32 v100, v111, 0x3e0293ee, v151
	s_and_b64 vcc, s[34:35], vcc
	v_add_f32_e32 v99, v100, v99
	v_exp_f32_e32 v100, v15
	v_exp_f32_e32 v102, v156
	v_exp_f32_e32 v106, v157
	v_exp_f32_e32 v108, v101
	v_exp_f32_e32 v156, v158
	v_exp_f32_e32 v110, v103
	v_cndmask_b32_e32 v98, v98, v210, vcc
	v_cmp_lt_i32_e32 vcc, s0, v0
	s_and_b64 vcc, s[34:35], vcc
	v_exp_f32_e32 v168, v96
	v_cndmask_b32_e32 v99, v99, v210, vcc
	v_exp_f32_e32 v166, v97
	v_exp_f32_e32 v172, v98
	v_exp_f32_e32 v170, v99
	v_cvt_pk_bf16_f32 v96, v14, v100
	v_cvt_pk_bf16_f32 v97, v104, v102
	v_cvt_pk_bf16_f32 v98, v106, v108
	v_cvt_pk_bf16_f32 v99, v156, v110
	v_exp_f32_e32 v160, v159
	v_exp_f32_e32 v158, v105
	v_mfma_f32_32x32x16_bf16 v[64:79], v[6:9], v[96:99], v[64:79]
	ds_read_b64_tr_b16 v[6:7], v223 offset:49152
	ds_read_b64_tr_b16 v[8:9], v224 offset:49152
	v_exp_f32_e32 v164, v161
	v_exp_f32_e32 v162, v107
	v_cvt_pk_bf16_f32 v232, v160, v158
	v_cvt_pk_bf16_f32 v234, v168, v166
	v_cvt_pk_bf16_f32 v235, v172, v170
	v_cvt_pk_bf16_f32 v233, v164, v162
	v_mfma_f32_32x32x16_bf16 v[48:63], v[10:13], v[96:99], v[48:63]
	ds_read_b64_tr_b16 v[10:11], v217 offset:53248
	ds_read_b64_tr_b16 v[12:13], v218 offset:53248
	v_add_f32_e32 v0, 0, v14
	v_fmamk_f32 v15, v88, 0x3e0293ee, v151
	v_mfma_f32_32x32x16_bf16 v[32:47], v[2:5], v[96:99], v[32:47]
	ds_read_b64_tr_b16 v[2:3], v219 offset:53248
	ds_read_b64_tr_b16 v[4:5], v220 offset:53248
	s_waitcnt lgkmcnt(4)
	v_mfma_f32_32x32x16_bf16 v[16:31], v[6:9], v[96:99], v[16:31]
	ds_read_b64_tr_b16 v[6:7], v221 offset:53248
	ds_read_b64_tr_b16 v[8:9], v222 offset:53248
	s_waitcnt lgkmcnt(4)
	v_mfma_f32_32x32x16_bf16 v[64:79], v[10:13], v[232:235], v[64:79]
	ds_read_b64_tr_b16 v[10:11], v223 offset:53248
	ds_read_b64_tr_b16 v[12:13], v224 offset:53248
	ds_read_b64_tr_b16 v[236:237], v217 offset:57344
	ds_read_b64_tr_b16 v[238:239], v218 offset:57344
	ds_read_b64_tr_b16 v[240:241], v219 offset:57344
	ds_read_b64_tr_b16 v[242:243], v220 offset:57344
	ds_read_b64_tr_b16 v[96:97], v221 offset:57344
	ds_read_b64_tr_b16 v[98:99], v222 offset:57344
	s_waitcnt lgkmcnt(10)
	v_mfma_f32_32x32x16_bf16 v[48:63], v[2:5], v[232:235], v[48:63]
	ds_read_b128 v[2:5], v226 offset:384
	s_waitcnt lgkmcnt(9)
	v_mfma_f32_32x32x16_bf16 v[32:47], v[6:9], v[232:235], v[32:47]
	v_subrev_u32_e32 v6, 31, v227
	v_fmamk_f32 v7, v80, 0x3e0293ee, v151
	v_cmp_lt_i32_e32 vcc, 0, v6
	s_waitcnt lgkmcnt(0)
	v_add_f32_e32 v2, v7, v2
	s_and_b64 vcc, s[34:35], vcc
	v_cndmask_b32_e32 v7, v2, v210, vcc
	v_fmamk_f32 v2, v81, 0x3e0293ee, v151
	v_cmp_lt_i32_e32 vcc, -1, v6
	v_add_f32_e32 v2, v2, v3
	s_and_b64 vcc, s[34:35], vcc
	v_cndmask_b32_e32 v8, v2, v210, vcc
	v_fmamk_f32 v2, v82, 0x3e0293ee, v151
	v_cmp_lt_i32_e32 vcc, -2, v6
	v_add_f32_e32 v2, v2, v4
	s_and_b64 vcc, s[34:35], vcc
	v_cndmask_b32_e32 v9, v2, v210, vcc
	v_fmamk_f32 v2, v83, 0x3e0293ee, v151
	v_cmp_lt_i32_e32 vcc, -3, v6
	v_add_f32_e32 v2, v2, v5
	s_and_b64 vcc, s[34:35], vcc
	v_mfma_f32_32x32x16_bf16 v[16:31], v[10:13], v[232:235], v[16:31]
	v_cndmask_b32_e32 v10, v2, v210, vcc
	ds_read_b128 v[2:5], v226 offset:416
	v_fmamk_f32 v11, v84, 0x3e0293ee, v151
	v_cmp_lt_i32_e32 vcc, -8, v6
	s_and_b64 vcc, s[34:35], vcc
	v_fmamk_f32 v83, v92, 0x3e0293ee, v151
	s_waitcnt lgkmcnt(0)
	v_add_f32_e32 v2, v11, v2
	v_cndmask_b32_e32 v11, v2, v210, vcc
	v_fmamk_f32 v2, v85, 0x3e0293ee, v151
	v_cmp_lt_i32_e32 vcc, -9, v6
	v_add_f32_e32 v2, v2, v3
	s_and_b64 vcc, s[34:35], vcc
	v_cndmask_b32_e32 v12, v2, v210, vcc
	v_fmamk_f32 v2, v86, 0x3e0293ee, v151
	v_cmp_lt_i32_e32 vcc, -10, v6
	v_add_f32_e32 v2, v2, v4
	s_and_b64 vcc, s[34:35], vcc
	v_cndmask_b32_e32 v13, v2, v210, vcc
	v_fmamk_f32 v2, v87, 0x3e0293ee, v151
	v_cmp_lt_i32_e32 vcc, -11, v6
	v_add_f32_e32 v2, v2, v5
	s_and_b64 vcc, s[34:35], vcc
	v_cndmask_b32_e32 v14, v2, v210, vcc
	ds_read_b128 v[2:5], v226 offset:448
	v_cmp_lt_i32_e32 vcc, -16, v6
	s_and_b64 vcc, s[34:35], vcc
	v_exp_f32_e32 v101, v7
	v_exp_f32_e32 v105, v8
	s_waitcnt lgkmcnt(0)
; #define MFMA32(a, b, c) __builtin_amdgcn_mfma_f32_32x32x16_bf16((a), (b), (c), 0, 0, 0)
; __device__ __forceinline__ unsigned pk2(float lo, float hi) { const f32x2v v = {lo, hi}; return __builtin_bit_cast(unsigned, __builtin_convertvector(v, bf16x2v)); }
; __device__ __forceinline__ float fast_exp2(float x) { return __builtin_amdgcn_exp2f(x); }
; template <int MODE>
; __device__ __forceinline__ void attn_item(LAS unsigned char* lds, const AttnArgs& a, const int tid) {
;     ...
;                 float ls = 0.f;
; #pragma unroll
;                 for (int i = 0; i < 16; ++i) { const float pv = fast_exp2(s[kt][i]); s[kt][i] = pv; ls += pv; }
;                 l += ls;
; #pragma unroll
;                 for (int ss = 0; ss < 2; ++ss) { u32x4 w;
;                     w.x = pk2(s[kt][8 * ss + 0], s[kt][8 * ss + 1]); w.y = pk2(s[kt][8 * ss + 2], s[kt][8 * ss + 3]);
;                     w.z = pk2(s[kt][8 * ss + 4], s[kt][8 * ss + 5]); w.w = pk2(s[kt][8 * ss + 6], s[kt][8 * ss + 7]);
;                     pf[ss] = __builtin_bit_cast(bf16x8, w); }
; #pragma unroll
;                 for (int jj = 0; jj < 8; ++jj) { const int j = 8 * kt + jj;
;                     o[jj & 3] = MFMA32(vf[j % VD], pf[jj >> 2], o[jj & 3]);
;                     if (j + VD < 16) AT_VLD(j + VD); }
;             }
	v_add_f32_e32 v2, v15, v2
	v_cndmask_b32_e32 v15, v2, v210, vcc
	v_fmamk_f32 v2, v89, 0x3e0293ee, v151
	v_cmp_lt_i32_e32 vcc, s62, v6
	v_add_f32_e32 v2, v2, v3
	s_and_b64 vcc, s[34:35], vcc
	v_cndmask_b32_e32 v80, v2, v210, vcc
	v_fmamk_f32 v2, v90, 0x3e0293ee, v151
	v_cmp_lt_i32_e32 vcc, s63, v6
	v_add_f32_e32 v2, v2, v4
	s_and_b64 vcc, s[34:35], vcc
	v_cndmask_b32_e32 v81, v2, v210, vcc
	v_fmamk_f32 v2, v91, 0x3e0293ee, v151
	v_cmp_lt_i32_e32 vcc, s97, v6
	v_add_f32_e32 v2, v2, v5
	s_and_b64 vcc, s[34:35], vcc
	v_cndmask_b32_e32 v82, v2, v210, vcc
	ds_read_b128 v[2:5], v226 offset:480
	v_cmp_lt_i32_e32 vcc, s40, v6
	s_and_b64 vcc, s[34:35], vcc
	v_exp_f32_e32 v103, v9
	v_exp_f32_e32 v107, v10
	s_waitcnt lgkmcnt(0)
	v_add_f32_e32 v2, v83, v2
	v_cndmask_b32_e32 v83, v2, v210, vcc
	v_fmamk_f32 v2, v93, 0x3e0293ee, v151
	v_cmp_lt_i32_e32 vcc, s81, v6
	v_add_f32_e32 v2, v2, v3
	s_and_b64 vcc, s[34:35], vcc
	v_cndmask_b32_e32 v84, v2, v210, vcc
	v_fmamk_f32 v2, v94, 0x3e0293ee, v151
	v_cmp_lt_i32_e32 vcc, s23, v6
	v_add_f32_e32 v2, v2, v4
	s_and_b64 vcc, s[34:35], vcc
	v_cndmask_b32_e32 v4, v2, v210, vcc
	v_fmamk_f32 v2, v95, 0x3e0293ee, v151
	v_cmp_lt_i32_e32 vcc, s0, v6
	v_add_f32_e32 v2, v2, v5
	s_and_b64 vcc, s[34:35], vcc
	v_cndmask_b32_e32 v5, v2, v210, vcc
	v_add_f32_e32 v2, v100, v0
	v_add_f32_e32 v3, v101, v1
	v_exp_f32_e32 v109, v11
	v_add_f32_e32 v2, v104, v2
	v_add_f32_e32 v3, v105, v3
	v_exp_f32_e32 v157, v12
	v_add_f32_e32 v2, v102, v2
	v_add_f32_e32 v3, v103, v3
	v_exp_f32_e32 v111, v13
	v_add_f32_e32 v2, v106, v2
	v_add_f32_e32 v3, v107, v3
	v_exp_f32_e32 v161, v14
	ds_read_b64_tr_b16 v[10:11], v223 offset:57344
	ds_read_b64_tr_b16 v[12:13], v224 offset:57344
	v_exp_f32_e32 v159, v15
	v_add_f32_e32 v2, v108, v2
	v_add_f32_e32 v3, v109, v3
	v_exp_f32_e32 v165, v80
	v_add_f32_e32 v2, v156, v2
	v_add_f32_e32 v3, v157, v3
	v_exp_f32_e32 v163, v81
	v_add_f32_e32 v2, v110, v2
	v_add_f32_e32 v3, v111, v3
	v_exp_f32_e32 v169, v82
	v_add_f32_e32 v2, v160, v2
	v_add_f32_e32 v3, v161, v3
	v_cvt_pk_bf16_f32 v6, v101, v105
	v_cvt_pk_bf16_f32 v7, v103, v107
	v_cvt_pk_bf16_f32 v8, v109, v157
	v_cvt_pk_bf16_f32 v9, v111, v161
	v_exp_f32_e32 v167, v83
	v_add_f32_e32 v2, v158, v2
	v_add_f32_e32 v3, v159, v3
	v_mfma_f32_32x32x16_bf16 v[64:79], v[236:239], v[6:9], v[64:79]
	v_exp_f32_e32 v173, v84
	v_add_f32_e32 v2, v164, v2
	v_add_f32_e32 v3, v165, v3
	v_exp_f32_e32 v171, v4
	v_add_f32_e32 v2, v162, v2
	v_add_f32_e32 v3, v163, v3
	v_exp_f32_e32 v155, v5
	v_add_f32_e32 v2, v168, v2
	v_add_f32_e32 v3, v169, v3
	ds_read_b64_tr_b16 v[84:85], v217 offset:61440
	ds_read_b64_tr_b16 v[86:87], v218 offset:61440
	v_mfma_f32_32x32x16_bf16 v[48:63], v[240:243], v[6:9], v[48:63]
	ds_read_b64_tr_b16 v[80:81], v219 offset:61440
	ds_read_b64_tr_b16 v[82:83], v220 offset:61440
	v_add_f32_e64 v2, v166, v2
	v_add_f32_e64 v3, v167, v3
	v_cvt_pk_bf16_f32 v4, v167, v173
	v_add_f32_e32 v2, v172, v2
	v_add_f32_e32 v3, v173, v3
	v_cvt_pk_bf16_f32 v5, v171, v155
	v_add_f32_e32 v2, v170, v2
	v_add_f32_e32 v3, v171, v3
	v_mfma_f32_32x32x16_bf16 v[32:47], v[96:99], v[6:9], v[32:47]
	v_add_f32_e64 v14, v154, v2
	v_add_f32_e64 v15, v155, v3
	v_cvt_pk_bf16_f32 v2, v159, v165
	v_cvt_pk_bf16_f32 v3, v163, v169
	v_add_f32_e32 v154, v14, v15
	s_waitcnt lgkmcnt(4)
	v_mfma_f32_32x32x16_bf16 v[16:31], v[10:13], v[6:9], v[16:31]
	ds_read_b64_tr_b16 v[6:7], v221 offset:61440
	ds_read_b64_tr_b16 v[8:9], v222 offset:61440
	ds_read_b64_tr_b16 v[10:11], v223 offset:61440
	ds_read_b64_tr_b16 v[12:13], v224 offset:61440
	s_waitcnt lgkmcnt(6)
	v_mfma_f32_32x32x16_bf16 v[64:79], v[84:87], v[2:5], v[64:79]
	s_waitcnt lgkmcnt(4)
	v_mfma_f32_32x32x16_bf16 v[48:63], v[80:83], v[2:5], v[48:63]
	s_waitcnt lgkmcnt(2)
	v_mfma_f32_32x32x16_bf16 v[32:47], v[6:9], v[2:5], v[32:47]
	s_waitcnt lgkmcnt(0)
	v_mfma_f32_32x32x16_bf16 v[16:31], v[10:13], v[2:5], v[16:31]

; template <int MODE>
; __device__ __forceinline__ void attn_item(LAS unsigned char* lds, const AttnArgs& a, const int tid) {
;     ...
;         if (t <= tw) {
;             LAS unsigned char* kb = lds + b * 32768;
;             f32x16 s[2];
; #pragma unroll
;             for (int i = 0; i < 16; ++i) { s[0][i] = 0.f; s[1][i] = 0.f; }
;             constexpr int KD = AT_KD, VD = AT_VD;
;             bf16x8 kf[KD];
;     ...
; #pragma unroll
;             for (int i = 0; i < KD; ++i) kf[i] = AT_KLD(i);
; #pragma unroll
;             for (int i = 0; i < 2 * NKS; ++i) { s[i & 1] = MFMA32(kf[i % KD], qf[i >> 1], s[i & 1]); if (i + KD < 2 * NKS) kf[i % KD] = AT_KLD(i + KD); }
;     ...
;             bf16x8 vf[VD];
;     ...
; #pragma unroll
;             for (int j = 0; j < VD; ++j) AT_VLD(j);
;             const float sc = a.sc;
;             const bool diag = (MODE == 1) && (t * 64 + 63 > qw0);
;             const bool near = (MODE == 2) && (t >= tw - 2);
;             bf16x8 pf[2];
; #pragma unroll
;             for (int kt = 0; kt < 2; ++kt) {
;                 if (MODE == 1) {
;                     const LAS float* csb = (const LAS float*)(lds + A_CS) + t * 64 + 32 * kt + 4 * h;
;                     const int mb = t * 64 + 32 * kt + 4 * h - (qw0 + r);
; #pragma unroll
;                     for (int g = 0; g < 4; ++g) { const f32x4 cv = *(const LAS f32x4*)(csb + 8 * g);
; #pragma unroll
;                         for (int e = 0; e < 4; ++e) { float x = fmaf(s[kt][4 * g + e], sc, addc) + cv[e]; if (diag && (mb + 8 * g + e > 0)) x = -1e30f; s[kt][4 * g + e] = x; } }
;                 } else if (MODE == 2) {
;                     if (near) {
;                         const LAS float* lut = (const LAS float*)(lds + A_LUT) + (t * 64 + 32 * kt + 4 * h - (qw0 + r) + 191);
; #pragma unroll
;                         for (int i = 0; i < 16; ++i) s[kt][i] = fmaf(s[kt][i], sc, lut[8 * (i >> 2) + (i & 3)]);
;                     } else {
; #pragma unroll
;                         for (int i = 0; i < 16; ++i) s[kt][i] = fmaf(s[kt][i], sc, addc);
;                     }
;                 } else {
; #pragma unroll
;                     for (int i = 0; i < 16; ++i) s[kt][i] = fmaf(s[kt][i], sc, addc);
;                 }
;                 float ls = 0.f;
; #pragma unroll
;                 for (int i = 0; i < 16; ++i) { const float pv = fast_exp2(s[kt][i]); s[kt][i] = pv; ls += pv; }
;                 l += ls;
.LBB0_95:
	v_add_f32_e32 v66, 0, v82
	v_add_f32_e32 v66, v83, v66
	v_add_f32_e32 v67, 0, v70
	v_add_f32_e32 v66, v84, v66
	v_add_f32_e32 v67, v71, v67
	v_add_f32_e32 v66, v85, v66
	v_add_f32_e32 v67, v72, v67
	v_add_f32_e32 v66, v86, v66
	v_add_f32_e32 v67, v73, v67
	v_add_f32_e32 v66, v87, v66
	v_add_f32_e32 v67, v141, v67
	v_add_f32_e32 v66, v88, v66
	v_add_f32_e32 v67, v165, v67
	v_add_f32_e32 v66, v89, v66
	v_add_f32_e32 v67, v166, v67
	v_add_f32_e32 v66, v90, v66
	v_add_f32_e32 v67, v167, v67
	v_add_f32_e32 v66, v91, v66
	v_add_f32_e32 v67, v74, v67
	v_add_f32_e32 v66, v92, v66
	v_add_f32_e32 v67, v75, v67
	v_add_f32_e32 v66, v93, v66
	v_add_f32_e32 v67, v76, v67
	v_add_f32_e32 v66, v94, v66
	v_add_f32_e32 v67, v77, v67
	v_add_f32_e32 v66, v95, v66
	v_add_f32_e32 v67, v78, v67
	v_add_f32_e32 v66, v96, v66
	v_add_f32_e32 v67, v79, v67
	v_add_f32_e32 v66, v97, v66
	v_add_f32_e32 v67, v80, v67
	v_add_f32_e32 v66, v140, v66
	v_add_f32_e32 v67, v81, v67
	v_add_f32_e32 v140, v66, v67
	ds_read_b128 v[66:69], v149 offset:32768
	ds_read_b128 v[70:73], v149 offset:40960
	ds_read_b128 v[166:169], v150 offset:32768
	ds_read_b128 v[170:173], v150 offset:40960
	s_waitcnt lgkmcnt(3)
	v_mfma_f32_32x32x16_bf16 v[82:97], v[66:69], v[98:101], 0
	ds_read_b128 v[184:187], v151 offset:32768
	ds_read_b128 v[188:191], v151 offset:40960
	s_xor_b64 s[6:7], s[8:9], -1
	s_mov_b64 s[10:11], 0xc0000
	s_mov_b64 s[8:9], 0
	s_and_b64 vcc, exec, s[6:7]
	s_waitcnt lgkmcnt(3)
	v_mfma_f32_32x32x16_bf16 v[82:97], v[166:169], v[102:105], v[82:97]
	ds_read_b128 v[166:169], v152 offset:32768
	v_mfma_f32_32x32x16_bf16 v[66:81], v[70:73], v[98:101], 0
	s_waitcnt lgkmcnt(2)
	v_mfma_f32_32x32x16_bf16 v[82:97], v[184:187], v[106:109], v[82:97]
	ds_read_b128 v[184:187], v153 offset:32768
	v_mfma_f32_32x32x16_bf16 v[66:81], v[170:173], v[102:105], v[66:81]
	ds_read_b128 v[170:173], v152 offset:40960
	s_waitcnt lgkmcnt(2)
	v_mfma_f32_32x32x16_bf16 v[82:97], v[166:169], v[110:113], v[82:97]
	ds_read_b128 v[166:169], v154 offset:32768
	v_mfma_f32_32x32x16_bf16 v[66:81], v[188:191], v[106:109], v[66:81]
	ds_read_b128 v[188:191], v153 offset:40960
	s_waitcnt lgkmcnt(3)
	v_mfma_f32_32x32x16_bf16 v[82:97], v[184:187], v[114:117], v[82:97]
	ds_read_b128 v[184:187], v155 offset:32768
	s_waitcnt lgkmcnt(3)
	v_mfma_f32_32x32x16_bf16 v[66:81], v[170:173], v[110:113], v[66:81]
	ds_read_b128 v[170:173], v154 offset:40960
	s_waitcnt lgkmcnt(3)
	v_mfma_f32_32x32x16_bf16 v[82:97], v[166:169], v[118:121], v[82:97]
	ds_read_b128 v[166:169], v156 offset:32768
	s_waitcnt lgkmcnt(3)
	v_mfma_f32_32x32x16_bf16 v[66:81], v[188:191], v[114:117], v[66:81]
	ds_read_b128 v[188:191], v155 offset:40960
	s_waitcnt lgkmcnt(3)
	v_mfma_f32_32x32x16_bf16 v[82:97], v[184:187], v[122:125], v[82:97]
	s_waitcnt lgkmcnt(2)
	v_mfma_f32_32x32x16_bf16 v[66:81], v[170:173], v[118:121], v[66:81]
	ds_read_b128 v[170:173], v156 offset:40960
	s_waitcnt lgkmcnt(2)
	v_mfma_f32_32x32x16_bf16 v[82:97], v[166:169], v[126:129], v[82:97]
	s_waitcnt lgkmcnt(1)
	v_mfma_f32_32x32x16_bf16 v[66:81], v[188:191], v[122:125], v[66:81]
	s_nop 9
	v_fmamk_f32 v82, v82, 0x3e0293ee, v147
	v_fmamk_f32 v83, v83, 0x3e0293ee, v147
	v_exp_f32_e32 v82, v82
	v_fmamk_f32 v84, v84, 0x3e0293ee, v147
	v_exp_f32_e32 v83, v83
	v_fmamk_f32 v85, v85, 0x3e0293ee, v147
	v_fmamk_f32 v86, v86, 0x3e0293ee, v147
	v_fmamk_f32 v87, v87, 0x3e0293ee, v147
	v_fmamk_f32 v88, v88, 0x3e0293ee, v147
	v_fmamk_f32 v89, v89, 0x3e0293ee, v147
	v_fmamk_f32 v90, v90, 0x3e0293ee, v147
	v_fmamk_f32 v91, v91, 0x3e0293ee, v147
	v_fmamk_f32 v92, v92, 0x3e0293ee, v147
	v_fmamk_f32 v93, v93, 0x3e0293ee, v147
	v_exp_f32_e32 v84, v84
	s_waitcnt lgkmcnt(0)
	v_mfma_f32_32x32x16_bf16 v[66:81], v[170:173], v[126:129], v[66:81]
	ds_read_b64_tr_b16 v[166:167], v157 offset:49152
	ds_read_b64_tr_b16 v[168:169], v158 offset:49152
	ds_read_b64_tr_b16 v[170:171], v159 offset:49152
	ds_read_b64_tr_b16 v[172:173], v160 offset:49152
	ds_read_b64_tr_b16 v[184:185], v161 offset:49152
	ds_read_b64_tr_b16 v[186:187], v162 offset:49152
	v_exp_f32_e32 v85, v85
	v_exp_f32_e32 v86, v86
	v_exp_f32_e32 v190, v87
	v_exp_f32_e32 v192, v88
	v_exp_f32_e32 v194, v89
	v_exp_f32_e32 v196, v90
	v_exp_f32_e32 v198, v91
	v_exp_f32_e32 v200, v92
	v_exp_f32_e32 v214, v93
	ds_read_b64_tr_b16 v[90:91], v163 offset:49152
	ds_read_b64_tr_b16 v[92:93], v164 offset:49152
	v_add_f32_e32 v141, 0, v82
	v_add_f32_e32 v141, v83, v141
	v_add_f32_e32 v141, v84, v141
	v_add_f32_e32 v141, v85, v141
	v_cvt_pk_bf16_f32 v82, v82, v83
	v_cvt_pk_bf16_f32 v83, v84, v85
	v_cvt_pk_bf16_f32 v84, v86, v190
	v_cvt_pk_bf16_f32 v85, v192, v194
	v_fmamk_f32 v94, v94, 0x3e0293ee, v147
	v_fmamk_f32 v95, v95, 0x3e0293ee, v147
	s_waitcnt lgkmcnt(6)
; #define MFMA32(a, b, c) __builtin_amdgcn_mfma_f32_32x32x16_bf16((a), (b), (c), 0, 0, 0)
; __device__ __forceinline__ unsigned pk2(float lo, float hi) { const f32x2v v = {lo, hi}; return __builtin_bit_cast(unsigned, __builtin_convertvector(v, bf16x2v)); }
; __device__ __forceinline__ float fast_exp2(float x) { return __builtin_amdgcn_exp2f(x); }
; template <int MODE>
; __device__ __forceinline__ void attn_item(LAS unsigned char* lds, const AttnArgs& a, const int tid) {
;     ...
;                 float ls = 0.f;
; #pragma unroll
;                 for (int i = 0; i < 16; ++i) { const float pv = fast_exp2(s[kt][i]); s[kt][i] = pv; ls += pv; }
;                 l += ls;
; #pragma unroll
;                 for (int ss = 0; ss < 2; ++ss) { u32x4 w;
;                     w.x = pk2(s[kt][8 * ss + 0], s[kt][8 * ss + 1]); w.y = pk2(s[kt][8 * ss + 2], s[kt][8 * ss + 3]);
;                     w.z = pk2(s[kt][8 * ss + 4], s[kt][8 * ss + 5]); w.w = pk2(s[kt][8 * ss + 6], s[kt][8 * ss + 7]);
;                     pf[ss] = __builtin_bit_cast(bf16x8, w); }
; #pragma unroll
;                 for (int jj = 0; jj < 8; ++jj) { const int j = 8 * kt + jj;
;                     o[jj & 3] = MFMA32(vf[j % VD], pf[jj >> 2], o[jj & 3]);
;                     if (j + VD < 16) AT_VLD(j + VD); }
;             }
;     ...
;         }
;         asm volatile("s_waitcnt vmcnt(0)" ::: "memory");
;         __syncthreads();
	v_mfma_f32_32x32x16_bf16 v[50:65], v[166:169], v[82:85], v[50:65]
	v_fmamk_f32 v96, v96, 0x3e0293ee, v147
	v_fmamk_f32 v97, v97, 0x3e0293ee, v147
	v_exp_f32_e32 v216, v94
	v_exp_f32_e32 v218, v95
	v_exp_f32_e32 v220, v96
	v_exp_f32_e32 v222, v97
	ds_read_b64_tr_b16 v[94:95], v157 offset:53248
	ds_read_b64_tr_b16 v[96:97], v158 offset:53248
	s_waitcnt lgkmcnt(6)
	v_mfma_f32_32x32x16_bf16 v[34:49], v[170:173], v[82:85], v[34:49]
	ds_read_b64_tr_b16 v[166:167], v159 offset:53248
	ds_read_b64_tr_b16 v[168:169], v160 offset:53248
	v_add_f32_e32 v188, v86, v141
	v_cvt_pk_bf16_f32 v86, v196, v198
	v_cvt_pk_bf16_f32 v87, v200, v214
	v_cvt_pk_bf16_f32 v88, v216, v218
	v_cvt_pk_bf16_f32 v89, v220, v222
	v_fmamk_f32 v66, v66, 0x3e0293ee, v147
	s_waitcnt lgkmcnt(6)
	v_mfma_f32_32x32x16_bf16 v[18:33], v[184:187], v[82:85], v[18:33]
	v_fmamk_f32 v67, v67, 0x3e0293ee, v147
	v_fmamk_f32 v68, v68, 0x3e0293ee, v147
	v_fmamk_f32 v69, v69, 0x3e0293ee, v147
	v_exp_f32_e32 v68, v68
	v_fmamk_f32 v70, v70, 0x3e0293ee, v147
	v_exp_f32_e32 v69, v69
	v_fmamk_f32 v71, v71, 0x3e0293ee, v147
	s_waitcnt lgkmcnt(4)
	v_mfma_f32_32x32x16_bf16 v[2:17], v[90:93], v[82:85], v[2:17]
	ds_read_b64_tr_b16 v[82:83], v161 offset:53248
	ds_read_b64_tr_b16 v[84:85], v162 offset:53248
	ds_read_b64_tr_b16 v[90:91], v163 offset:53248
	ds_read_b64_tr_b16 v[92:93], v164 offset:53248
	v_exp_f32_e32 v191, v70
	v_fmamk_f32 v72, v72, 0x3e0293ee, v147
	v_exp_f32_e32 v193, v71
	v_fmamk_f32 v73, v73, 0x3e0293ee, v147
	v_fmamk_f32 v78, v78, 0x3e0293ee, v147
	s_waitcnt lgkmcnt(6)
	v_mfma_f32_32x32x16_bf16 v[50:65], v[94:97], v[86:89], v[50:65]
	v_fmamk_f32 v79, v79, 0x3e0293ee, v147
	v_fmamk_f32 v80, v80, 0x3e0293ee, v147
	v_fmamk_f32 v81, v81, 0x3e0293ee, v147
	v_exp_f32_e32 v195, v72
	ds_read_b64_tr_b16 v[94:95], v157 offset:57344
	ds_read_b64_tr_b16 v[96:97], v158 offset:57344
	v_fmamk_f32 v74, v74, 0x3e0293ee, v147
	v_exp_f32_e32 v197, v73
	s_waitcnt lgkmcnt(6)
	v_mfma_f32_32x32x16_bf16 v[34:49], v[166:169], v[86:89], v[34:49]
	ds_read_b64_tr_b16 v[166:167], v159 offset:57344
	ds_read_b64_tr_b16 v[168:169], v160 offset:57344
	v_exp_f32_e32 v219, v78
	v_exp_f32_e32 v221, v79
	v_exp_f32_e32 v223, v80
	v_exp_f32_e32 v141, v81
	v_fmamk_f32 v75, v75, 0x3e0293ee, v147
	v_exp_f32_e32 v199, v74
	s_waitcnt lgkmcnt(6)
	v_mfma_f32_32x32x16_bf16 v[18:33], v[82:85], v[86:89], v[18:33]
	v_fmamk_f32 v76, v76, 0x3e0293ee, v147
	v_exp_f32_e32 v201, v75
	v_fmamk_f32 v77, v77, 0x3e0293ee, v147
	v_exp_f32_e32 v215, v76
	v_exp_f32_e32 v217, v77
	v_cvt_pk_bf16_f32 v75, v68, v69
	v_cvt_pk_bf16_f32 v76, v191, v193
	s_waitcnt lgkmcnt(4)
	v_mfma_f32_32x32x16_bf16 v[2:17], v[90:93], v[86:89], v[2:17]
	v_exp_f32_e32 v88, v66
	v_exp_f32_e32 v89, v67
	ds_read_b64_tr_b16 v[84:85], v161 offset:57344
	ds_read_b64_tr_b16 v[86:87], v162 offset:57344
	ds_read_b64_tr_b16 v[78:79], v163 offset:57344
	ds_read_b64_tr_b16 v[80:81], v164 offset:57344
	v_add_f32_e32 v66, 0, v88
	v_add_f32_e32 v66, v89, v66
	v_add_f32_e32 v66, v68, v66
	v_add_f32_e32 v189, v69, v66
	v_add_f32_e32 v66, v190, v188
	v_add_f32_e32 v67, v191, v189
	v_cvt_pk_bf16_f32 v74, v88, v89
	v_add_f32_e32 v66, v192, v66
	v_add_f32_e32 v67, v193, v67
	v_cvt_pk_bf16_f32 v77, v195, v197
	v_add_f32_e32 v66, v194, v66
	v_add_f32_e32 v67, v195, v67
	ds_read_b64_tr_b16 v[88:89], v157 offset:61440
	ds_read_b64_tr_b16 v[90:91], v158 offset:61440
	v_add_f32_e32 v66, v196, v66
	v_add_f32_e32 v67, v197, v67
	s_waitcnt lgkmcnt(8)
	v_mfma_f32_32x32x16_bf16 v[50:65], v[94:97], v[74:77], v[50:65]
	v_add_f32_e64 v66, v198, v66
	v_add_f32_e64 v67, v199, v67
	ds_read_b64_tr_b16 v[70:71], v159 offset:61440
	ds_read_b64_tr_b16 v[72:73], v160 offset:61440
	v_add_f32_e64 v66, v200, v66
	v_add_f32_e64 v67, v201, v67
	v_cvt_pk_bf16_f32 v68, v219, v221
	v_add_f32_e32 v66, v214, v66
	v_add_f32_e32 v67, v215, v67
	v_cvt_pk_bf16_f32 v69, v223, v141
	v_add_f32_e32 v66, v216, v66
	v_add_f32_e32 v67, v217, v67
	s_waitcnt lgkmcnt(8)
	v_mfma_f32_32x32x16_bf16 v[34:49], v[166:169], v[74:77], v[34:49]
	v_add_f32_e64 v66, v218, v66
	v_add_f32_e64 v67, v219, v67
	v_add_f32_e64 v66, v220, v66
	v_add_f32_e64 v67, v221, v67
	v_add_f32_e64 v66, v222, v66
	v_add_f32_e64 v67, v223, v67
	v_add_f32_e32 v82, v140, v66
	v_add_f32_e32 v83, v141, v67
	s_waitcnt lgkmcnt(6)
	v_mfma_f32_32x32x16_bf16 v[18:33], v[84:87], v[74:77], v[18:33]
	v_cvt_pk_bf16_f32 v66, v199, v201
	v_cvt_pk_bf16_f32 v67, v215, v217
	v_add_f32_e32 v140, v82, v83
	s_waitcnt lgkmcnt(4)
	v_mfma_f32_32x32x16_bf16 v[2:17], v[78:81], v[74:77], v[2:17]
	ds_read_b64_tr_b16 v[74:75], v161 offset:61440
	ds_read_b64_tr_b16 v[76:77], v162 offset:61440
	ds_read_b64_tr_b16 v[78:79], v163 offset:61440
	ds_read_b64_tr_b16 v[80:81], v164 offset:61440
	s_waitcnt vmcnt(0)
	s_waitcnt lgkmcnt(0)
	s_barrier
	v_mfma_f32_32x32x16_bf16 v[50:65], v[88:91], v[66:69], v[50:65]
	v_mfma_f32_32x32x16_bf16 v[34:49], v[70:73], v[66:69], v[34:49]
	v_mfma_f32_32x32x16_bf16 v[18:33], v[74:77], v[66:69], v[18:33]
	v_mfma_f32_32x32x16_bf16 v[2:17], v[78:81], v[66:69], v[2:17]
	s_cbranch_vccnz .LBB0_98

;     __device__ __forceinline__ void operator()(const f32x4 (&acc)[2][2][4][2], const pg8::Unit& u, int wr, int wc, int fr, int fq) const {
;     ...
;                     for (int bj = 0; bj < 2; ++bj) { const f32x4 a0 = acc[ai][bj][m][0], a1 = acc[ai][bj][m][1];
;                         float ss = (a0[0] * a0[0] + a0[1] * a0[1]) + (a0[2] * a0[2] + a0[3] * a0[3]) + (a1[0] * a1[0] + a1[1] * a1[1]) + (a1[2] * a1[2] + a1[3] * a1[3]);
;                         ss += __shfl_xor(ss, 16); ss += __shfl_xor(ss, 32);
;                         if (fq == 0) part[(lrow0 + ai * 128 + m * 16) * 8 + bj * 4 + wc] = ss; }
.LBB0_258:
	s_cmp_lg_u32 s1, 0
	s_cselect_b64 s[8:9], -1, 0
	s_cmp_eq_u32 s1, 0
	v_lshlrev_b32_e32 v184, 5, v0
	s_cbranch_scc1 .LBB0_293
	v_mul_f32_e32 v91, v63, v63
	v_mul_f32_e32 v92, v65, v65
	v_fmac_f32_e32 v91, v62, v62
	v_fmac_f32_e32 v92, v64, v64
	v_and_b32_e32 v90, 64, v204
	v_add_f32_e32 v91, v91, v92
	v_mul_f32_e32 v92, v59, v59
	v_xor_b32_e32 v0, 16, v204
	v_add_u32_e32 v90, 64, v90
	v_fmac_f32_e32 v92, v58, v58
	v_cmp_lt_i32_e32 vcc, v0, v90
	v_add_f32_e32 v91, v91, v92
	v_mul_f32_e32 v92, v61, v61
	v_cndmask_b32_e32 v0, v204, v0, vcc
	v_fmac_f32_e32 v92, v60, v60
	v_lshlrev_b32_e32 v0, 2, v0
	v_add_f32_e32 v91, v92, v91
	v_mov_b32_e32 v92, v91
	s_nop 1
	v_permlane16_swap_b32_e32 v92, v91
	v_xor_b32_e32 v93, 32, v204
	v_cmp_lt_i32_e32 vcc, v93, v90
	v_readlane_b32 s10, v250, 31
	s_waitcnt lgkmcnt(0)
	v_add_f32_e32 v92, v91, v92
	v_cndmask_b32_e32 v90, v204, v93, vcc
	v_lshlrev_b32_e32 v90, 2, v90
	v_mov_b32_e32 v93, v92
	s_nop 1
	v_permlane32_swap_b32_e32 v93, v92
	v_cmp_eq_u32_e32 vcc, 0, v179
	v_add_u32_e32 v91, s10, v184
	s_and_saveexec_b64 s[10:11], vcc
	s_cbranch_execz .LBB0_261
	s_waitcnt lgkmcnt(0)
	v_add_f32_e32 v92, v92, v93
	ds_write_b32 v91, v92
.LBB0_261:
	s_or_b64 exec, exec, s[10:11]
	v_mul_f32_e32 v92, v135, v135
	s_waitcnt lgkmcnt(0)
	v_mul_f32_e32 v93, v137, v137
	v_fmac_f32_e32 v92, v134, v134
	v_fmac_f32_e32 v93, v136, v136
	v_add_f32_e32 v92, v92, v93
	v_mul_f32_e32 v93, v131, v131
	v_fmac_f32_e32 v93, v130, v130
	v_add_f32_e32 v92, v92, v93
	v_mul_f32_e32 v93, v133, v133
	v_fmac_f32_e32 v93, v132, v132
	v_add_f32_e32 v92, v93, v92
	v_mov_b32_e32 v93, v92
	s_nop 1
	v_permlane16_swap_b32_e32 v93, v92
	s_waitcnt lgkmcnt(0)
	v_add_f32_e32 v92, v92, v93
	v_mov_b32_e32 v93, v92
	s_nop 1
	v_permlane32_swap_b32_e32 v93, v92
	s_and_saveexec_b64 s[10:11], vcc
	s_cbranch_execz .LBB0_263
	s_waitcnt lgkmcnt(0)
	v_add_f32_e32 v92, v92, v93
	ds_write_b32 v91, v92 offset:16
.LBB0_263:
	s_or_b64 exec, exec, s[10:11]
	v_mul_f32_e32 v91, v55, v55
	v_mul_f32_e32 v92, v57, v57
	v_fmac_f32_e32 v91, v54, v54
	v_fmac_f32_e32 v92, v56, v56
	v_add_f32_e32 v91, v91, v92
	v_mul_f32_e32 v92, v51, v51
	v_fmac_f32_e32 v92, v50, v50
	v_add_f32_e32 v91, v91, v92
	v_mul_f32_e32 v92, v53, v53
	v_fmac_f32_e32 v92, v52, v52
	v_add_f32_e32 v91, v92, v91
	v_mov_b32_e32 v92, v91
	s_nop 1
	v_permlane16_swap_b32_e32 v92, v91
	v_readlane_b32 s10, v250, 32
	s_waitcnt lgkmcnt(0)
	v_add_f32_e32 v92, v91, v92
	v_mov_b32_e32 v93, v92
	s_nop 1
	v_permlane32_swap_b32_e32 v93, v92
	v_add_u32_e32 v91, s10, v184
	s_and_saveexec_b64 s[10:11], vcc
	s_cbranch_execz .LBB0_265
	s_waitcnt lgkmcnt(0)
	v_add_f32_e32 v92, v92, v93
	ds_write_b32 v91, v92
.LBB0_265:
	s_or_b64 exec, exec, s[10:11]
	v_mul_f32_e32 v92, v127, v127
	s_waitcnt lgkmcnt(0)
	v_mul_f32_e32 v93, v129, v129
	v_fmac_f32_e32 v92, v126, v126
	v_fmac_f32_e32 v93, v128, v128
	v_add_f32_e32 v92, v92, v93
	v_mul_f32_e32 v93, v123, v123
	v_fmac_f32_e32 v93, v122, v122
	v_add_f32_e32 v92, v92, v93
	v_mul_f32_e32 v93, v125, v125
	v_fmac_f32_e32 v93, v124, v124
	v_add_f32_e32 v92, v93, v92
	v_mov_b32_e32 v93, v92
	s_nop 1
	v_permlane16_swap_b32_e32 v93, v92
	s_waitcnt lgkmcnt(0)
	v_add_f32_e32 v92, v92, v93
	v_mov_b32_e32 v93, v92
	s_nop 1
	v_permlane32_swap_b32_e32 v93, v92
	s_and_saveexec_b64 s[10:11], vcc
	s_cbranch_execz .LBB0_267
	s_waitcnt lgkmcnt(0)
	v_add_f32_e32 v92, v92, v93
	ds_write_b32 v91, v92 offset:16
.LBB0_267:
	s_or_b64 exec, exec, s[10:11]
	v_mul_f32_e32 v91, v47, v47
	v_mul_f32_e32 v92, v49, v49
	v_fmac_f32_e32 v91, v46, v46
	v_fmac_f32_e32 v92, v48, v48
	v_add_f32_e32 v91, v91, v92
	v_mul_f32_e32 v92, v43, v43
	v_fmac_f32_e32 v92, v42, v42
	v_add_f32_e32 v91, v91, v92
	v_mul_f32_e32 v92, v45, v45
	v_fmac_f32_e32 v92, v44, v44
	v_add_f32_e32 v91, v92, v91
	v_mov_b32_e32 v92, v91
	s_nop 1
	v_permlane16_swap_b32_e32 v92, v91
	v_readlane_b32 s10, v250, 33
	s_waitcnt lgkmcnt(0)
	v_add_f32_e32 v92, v91, v92
	v_mov_b32_e32 v93, v92
	s_nop 1
	v_permlane32_swap_b32_e32 v93, v92
	v_add_u32_e32 v91, s10, v184
	s_and_saveexec_b64 s[10:11], vcc
	s_cbranch_execz .LBB0_269
	s_waitcnt lgkmcnt(0)
	v_add_f32_e32 v92, v92, v93
	ds_write_b32 v91, v92
.LBB0_269:
	s_or_b64 exec, exec, s[10:11]
	v_mul_f32_e32 v92, v119, v119
	s_waitcnt lgkmcnt(0)
	v_mul_f32_e32 v93, v121, v121
	v_fmac_f32_e32 v92, v118, v118
	v_fmac_f32_e32 v93, v120, v120
	v_add_f32_e32 v92, v92, v93
	v_mul_f32_e32 v93, v115, v115
	v_fmac_f32_e32 v93, v114, v114
	v_add_f32_e32 v92, v92, v93
	v_mul_f32_e32 v93, v117, v117
	v_fmac_f32_e32 v93, v116, v116
	v_add_f32_e32 v92, v93, v92
	v_mov_b32_e32 v93, v92
	s_nop 1
	v_permlane16_swap_b32_e32 v93, v92
	s_waitcnt lgkmcnt(0)
	v_add_f32_e32 v92, v92, v93
	v_mov_b32_e32 v93, v92
	s_nop 1
	v_permlane32_swap_b32_e32 v93, v92
	s_and_saveexec_b64 s[10:11], vcc
	s_cbranch_execz .LBB0_271
	s_waitcnt lgkmcnt(0)
	v_add_f32_e32 v92, v92, v93
	ds_write_b32 v91, v92 offset:16
.LBB0_271:
	s_or_b64 exec, exec, s[10:11]
	v_mul_f32_e32 v91, v39, v39
	v_mul_f32_e32 v92, v41, v41
	v_fmac_f32_e32 v91, v38, v38
	v_fmac_f32_e32 v92, v40, v40
	v_add_f32_e32 v91, v91, v92
	v_mul_f32_e32 v92, v35, v35
	v_fmac_f32_e32 v92, v34, v34
	v_add_f32_e32 v91, v91, v92
	v_mul_f32_e32 v92, v37, v37
	v_fmac_f32_e32 v92, v36, v36
	v_add_f32_e32 v91, v92, v91
	v_mov_b32_e32 v92, v91
	s_nop 1
	v_permlane16_swap_b32_e32 v92, v91
	v_readlane_b32 s10, v250, 34
	s_waitcnt lgkmcnt(0)
	v_add_f32_e32 v92, v91, v92
	v_mov_b32_e32 v93, v92
	s_nop 1
	v_permlane32_swap_b32_e32 v93, v92
	v_add_u32_e32 v91, s10, v184
	s_and_saveexec_b64 s[10:11], vcc
	s_cbranch_execz .LBB0_273
	s_waitcnt lgkmcnt(0)
	v_add_f32_e32 v92, v92, v93
	ds_write_b32 v91, v92
;     __device__ __forceinline__ void operator()(const f32x4 (&acc)[2][2][4][2], const pg8::Unit& u, int wr, int wc, int fr, int fq) const {
;     ...
;                     for (int bj = 0; bj < 2; ++bj) { const f32x4 a0 = acc[ai][bj][m][0], a1 = acc[ai][bj][m][1];
;                         float ss = (a0[0] * a0[0] + a0[1] * a0[1]) + (a0[2] * a0[2] + a0[3] * a0[3]) + (a1[0] * a1[0] + a1[1] * a1[1]) + (a1[2] * a1[2] + a1[3] * a1[3]);
;                         ss += __shfl_xor(ss, 16); ss += __shfl_xor(ss, 32);
;                         if (fq == 0) part[(lrow0 + ai * 128 + m * 16) * 8 + bj * 4 + wc] = ss; }
.LBB0_273:
	s_or_b64 exec, exec, s[10:11]
	v_mul_f32_e32 v92, v111, v111
	s_waitcnt lgkmcnt(0)
	v_mul_f32_e32 v93, v113, v113
	v_fmac_f32_e32 v92, v110, v110
	v_fmac_f32_e32 v93, v112, v112
	v_add_f32_e32 v92, v92, v93
	v_mul_f32_e32 v93, v107, v107
	v_fmac_f32_e32 v93, v106, v106
	v_add_f32_e32 v92, v92, v93
	v_mul_f32_e32 v93, v109, v109
	v_fmac_f32_e32 v93, v108, v108
	v_add_f32_e32 v92, v93, v92
	v_mov_b32_e32 v93, v92
	s_nop 1
	v_permlane16_swap_b32_e32 v93, v92
	s_waitcnt lgkmcnt(0)
	v_add_f32_e32 v92, v92, v93
	v_mov_b32_e32 v93, v92
	s_nop 1
	v_permlane32_swap_b32_e32 v93, v92
	s_and_saveexec_b64 s[10:11], vcc
	s_cbranch_execz .LBB0_275
	s_waitcnt lgkmcnt(0)
	v_add_f32_e32 v92, v92, v93
	ds_write_b32 v91, v92 offset:16
.LBB0_275:
	s_or_b64 exec, exec, s[10:11]
	v_mul_f32_e32 v91, v31, v31
	v_mul_f32_e32 v92, v33, v33
	v_fmac_f32_e32 v91, v30, v30
	v_fmac_f32_e32 v92, v32, v32
	v_add_f32_e32 v91, v91, v92
	v_mul_f32_e32 v92, v27, v27
	v_fmac_f32_e32 v92, v26, v26
	v_add_f32_e32 v91, v91, v92
	v_mul_f32_e32 v92, v29, v29
	v_fmac_f32_e32 v92, v28, v28
	v_add_f32_e32 v91, v92, v91
	v_mov_b32_e32 v92, v91
	s_nop 1
	v_permlane16_swap_b32_e32 v92, v91
	v_readlane_b32 s10, v250, 35
	s_waitcnt lgkmcnt(0)
	v_add_f32_e32 v92, v91, v92
	v_mov_b32_e32 v93, v92
	s_nop 1
	v_permlane32_swap_b32_e32 v93, v92
	v_add_u32_e32 v91, s10, v184
	s_and_saveexec_b64 s[10:11], vcc
	s_cbranch_execz .LBB0_277
	s_waitcnt lgkmcnt(0)
	v_add_f32_e32 v92, v92, v93
	ds_write_b32 v91, v92
.LBB0_277:
	s_or_b64 exec, exec, s[10:11]
	v_mul_f32_e32 v92, v103, v103
	s_waitcnt lgkmcnt(0)
	v_mul_f32_e32 v93, v105, v105
	v_fmac_f32_e32 v92, v102, v102
	v_fmac_f32_e32 v93, v104, v104
	v_add_f32_e32 v92, v92, v93
	v_mul_f32_e32 v93, v99, v99
	v_fmac_f32_e32 v93, v98, v98
	v_add_f32_e32 v92, v92, v93
	v_mul_f32_e32 v93, v101, v101
	v_fmac_f32_e32 v93, v100, v100
	v_add_f32_e32 v92, v93, v92
	v_mov_b32_e32 v93, v92
	s_nop 1
	v_permlane16_swap_b32_e32 v93, v92
	s_waitcnt lgkmcnt(0)
	v_add_f32_e32 v92, v92, v93
	v_mov_b32_e32 v93, v92
	s_nop 1
	v_permlane32_swap_b32_e32 v93, v92
	s_and_saveexec_b64 s[10:11], vcc
	s_cbranch_execz .LBB0_279
	s_waitcnt lgkmcnt(0)
	v_add_f32_e32 v92, v92, v93
	ds_write_b32 v91, v92 offset:16
.LBB0_279:
	s_or_b64 exec, exec, s[10:11]
	v_mul_f32_e32 v91, v23, v23
	v_mul_f32_e32 v92, v25, v25
	v_fmac_f32_e32 v91, v22, v22
	v_fmac_f32_e32 v92, v24, v24
	v_add_f32_e32 v91, v91, v92
	v_mul_f32_e32 v92, v19, v19
	v_fmac_f32_e32 v92, v18, v18
	v_add_f32_e32 v91, v91, v92
	v_mul_f32_e32 v92, v21, v21
	v_fmac_f32_e32 v92, v20, v20
	v_add_f32_e32 v91, v92, v91
	v_mov_b32_e32 v92, v91
	s_nop 1
	v_permlane16_swap_b32_e32 v92, v91
	v_readlane_b32 s10, v250, 36
	s_waitcnt lgkmcnt(0)
	v_add_f32_e32 v92, v91, v92
	v_mov_b32_e32 v93, v92
	s_nop 1
	v_permlane32_swap_b32_e32 v93, v92
	v_add_u32_e32 v91, s10, v184
	s_and_saveexec_b64 s[10:11], vcc
	s_cbranch_execz .LBB0_281
	s_waitcnt lgkmcnt(0)
	v_add_f32_e32 v92, v92, v93
	ds_write_b32 v91, v92
.LBB0_281:
	s_or_b64 exec, exec, s[10:11]
	v_mul_f32_e32 v92, v87, v87
	s_waitcnt lgkmcnt(0)
	v_mul_f32_e32 v93, v89, v89
	v_fmac_f32_e32 v92, v86, v86
	v_fmac_f32_e32 v93, v88, v88
	v_add_f32_e32 v92, v92, v93
	v_mul_f32_e32 v93, v83, v83
	v_fmac_f32_e32 v93, v82, v82
	v_add_f32_e32 v92, v92, v93
	v_mul_f32_e32 v93, v85, v85
	v_fmac_f32_e32 v93, v84, v84
	v_add_f32_e32 v92, v93, v92
	v_mov_b32_e32 v93, v92
	s_nop 1
	v_permlane16_swap_b32_e32 v93, v92
	s_waitcnt lgkmcnt(0)
	v_add_f32_e32 v92, v92, v93
	v_mov_b32_e32 v93, v92
	s_nop 1
	v_permlane32_swap_b32_e32 v93, v92
	s_and_saveexec_b64 s[10:11], vcc
	s_cbranch_execz .LBB0_283
	s_waitcnt lgkmcnt(0)
	v_add_f32_e32 v92, v92, v93
	ds_write_b32 v91, v92 offset:16
.LBB0_283:
	s_or_b64 exec, exec, s[10:11]
	v_mul_f32_e32 v91, v15, v15
	v_mul_f32_e32 v92, v17, v17
	v_fmac_f32_e32 v91, v14, v14
	v_fmac_f32_e32 v92, v16, v16
	v_add_f32_e32 v91, v91, v92
	v_mul_f32_e32 v92, v11, v11
	v_fmac_f32_e32 v92, v10, v10
	v_add_f32_e32 v91, v91, v92
	v_mul_f32_e32 v92, v13, v13
	v_fmac_f32_e32 v92, v12, v12
	v_add_f32_e32 v91, v92, v91
	v_mov_b32_e32 v92, v91
	s_nop 1
	v_permlane16_swap_b32_e32 v92, v91
	v_readlane_b32 s10, v250, 37
	s_waitcnt lgkmcnt(0)
	v_add_f32_e32 v92, v91, v92
	v_mov_b32_e32 v93, v92
	s_nop 1
	v_permlane32_swap_b32_e32 v93, v92
	v_add_u32_e32 v91, s10, v184
	s_and_saveexec_b64 s[10:11], vcc
	s_cbranch_execz .LBB0_285
	s_waitcnt lgkmcnt(0)
	v_add_f32_e32 v92, v92, v93
	ds_write_b32 v91, v92
.LBB0_285:
	s_or_b64 exec, exec, s[10:11]
	v_mul_f32_e32 v92, v79, v79
	s_waitcnt lgkmcnt(0)
	v_mul_f32_e32 v93, v81, v81
	v_fmac_f32_e32 v92, v78, v78
	v_fmac_f32_e32 v93, v80, v80
	v_add_f32_e32 v92, v92, v93
	v_mul_f32_e32 v93, v75, v75
	v_fmac_f32_e32 v93, v74, v74
	v_add_f32_e32 v92, v92, v93
	v_mul_f32_e32 v93, v77, v77
	v_fmac_f32_e32 v93, v76, v76
	v_add_f32_e32 v92, v93, v92
	v_mov_b32_e32 v93, v92
	s_nop 1
	v_permlane16_swap_b32_e32 v93, v92
	s_waitcnt lgkmcnt(0)
	v_add_f32_e32 v92, v92, v93
	v_mov_b32_e32 v93, v92
	s_nop 1
	v_permlane32_swap_b32_e32 v93, v92
	s_and_saveexec_b64 s[10:11], vcc
	s_cbranch_execz .LBB0_287
	s_waitcnt lgkmcnt(0)
	v_add_f32_e32 v92, v92, v93
	ds_write_b32 v91, v92 offset:16
.LBB0_287:
	s_or_b64 exec, exec, s[10:11]
	v_mul_f32_e32 v91, v7, v7
	v_mul_f32_e32 v92, v9, v9
	v_fmac_f32_e32 v91, v6, v6
	v_fmac_f32_e32 v92, v8, v8
	v_add_f32_e32 v91, v91, v92
	v_mul_f32_e32 v92, v3, v3
	v_fmac_f32_e32 v92, v2, v2
	v_add_f32_e32 v91, v91, v92
	v_mul_f32_e32 v92, v5, v5
	v_fmac_f32_e32 v92, v4, v4
	v_add_f32_e32 v91, v92, v91
	v_mov_b32_e32 v92, v91
	s_nop 1
	v_permlane16_swap_b32_e32 v92, v91
	v_readlane_b32 s10, v250, 38
	s_waitcnt lgkmcnt(0)
	v_add_f32_e32 v92, v91, v92
	v_mov_b32_e32 v93, v92
	s_nop 1
	v_permlane32_swap_b32_e32 v93, v92
	v_add_u32_e32 v91, s10, v184
	s_and_saveexec_b64 s[10:11], vcc
	s_cbranch_execz .LBB0_289
	s_waitcnt lgkmcnt(0)
	v_add_f32_e32 v92, v92, v93
	ds_write_b32 v91, v92
.LBB0_289:
	s_or_b64 exec, exec, s[10:11]
	v_mul_f32_e32 v92, v71, v71
	s_waitcnt lgkmcnt(0)
	v_mul_f32_e32 v93, v73, v73
	v_fmac_f32_e32 v92, v70, v70
	v_fmac_f32_e32 v93, v72, v72
	v_add_f32_e32 v92, v92, v93
	v_mul_f32_e32 v93, v67, v67
	v_fmac_f32_e32 v93, v66, v66
	v_add_f32_e32 v92, v92, v93
	v_mul_f32_e32 v93, v69, v69
	v_fmac_f32_e32 v93, v68, v68
	v_add_f32_e32 v92, v93, v92
	v_mov_b32_e32 v0, v92
	s_nop 1
	v_permlane16_swap_b32_e32 v0, v92
	s_waitcnt lgkmcnt(0)
	v_add_f32_e32 v0, v92, v0
	v_mov_b32_e32 v90, v0
	s_nop 1
	v_permlane32_swap_b32_e32 v90, v0
	s_and_saveexec_b64 s[10:11], vcc
	s_cbranch_execz .LBB0_291
	s_waitcnt lgkmcnt(0)
	v_add_f32_e32 v0, v0, v90
	ds_write_b32 v91, v0 offset:16
